# attention row sums on the 16x16x32 MFMA with a per-lane selector operand (half the matrix-pipe time of the 32x32 form, 12 fewer VGPRs)
# speedup vs baseline: 1.0163x; 1.0119x over previous
; template <bool MLA>
; DI void attn_phase(const int TID, const int BID, LAS unsigned char* lds, const Params& p, bool need_ctx) {
;     ...
;     const int tid = TID, wid = tid >> 6, lane = tid & 63, r = lane & 31, hh = lane >> 5;
;     const int n_items = 1024 + (need_ctx ? 128 : 0);
;     bf16_t* O = P_WSB(OFF_H);
;     for (int item = BID; item < n_items; item += gridDim.x) {
;         int b, head, row0, nk;
;         if (item < 1024) {
;             const int rnd = item >> 8, w = item & 255, xcd = w & 7, slot = w >> 3, qb = slot & 7;
;             if (MLA) { const int grp = (rnd * 8 + xcd) * 4 + (slot >> 3); b = grp >> 4; head = grp & 15; }
;             else { const int grp = rnd * 8 + xcd; b = grp >> 2; head = (grp & 3) * 4 + (slot >> 3); }
;             row0 = b * 2048 + qb * 256; nk = NKEY;
;         }
;         else { const int it = item - 1024; b = it >> 4; head = it & 15; row0 = TL + b * 256; nk = 256; }
;         const int kvh = MLA ? head : (head >> 2);
;         const bf16_t* Kb = P_WSB(OFF_K) + (size_t)(b * NKV + kvh) * NKEY * 64;
;         const bf16_t* Vb = P_WSB(OFF_VT) + (size_t)(b * NKV + kvh) * NKEY * 64;
;         const bf16_t* Pb = P_WSB(OFF_KPE) + (size_t)b * NKEY * 32;
;         bf16x8 qf[NKS];
;         {
;             const bf16_t* qp = P_WSB(OFF_Q) + (size_t)(row0 + wid * 32 + r) * QS + head * DK + hh * 8;
; #pragma unroll
;             for (int ks = 0; ks < NKS; ++ks) qf[ks] = *(const bf16x8*)(qp + ks * 16);
;         }
;         u32x4 kreg, vreg; u32x2 preg = {0u, 0u};
.LBB0_293:
	s_andn2_b64 vcc, exec, s[0:1]
	s_cbranch_vccnz .LBB0_773
	s_add_i32 s0, s23, 0x22040
	v_writelane_b32 v255, s0, 32
	s_nop 0
	v_readlane_b32 s0, v255, 21
	s_cmp_lt_i32 s0, 2
	s_mov_b64 s[0:1], -1
	s_cbranch_scc1 .LBB0_501
	v_readlane_b32 s0, v255, 21
	s_cmp_gt_i32 s0, 2
	v_readlane_b32 s0, v255, 24
	v_readlane_b32 s1, v255, 25
	s_mov_b64 s[2:3], -1
	s_nop 0
	v_cndmask_b32_e64 v0, 0, 1, s[0:1]
	v_cmp_ne_u32_e64 s[0:1], 1, v0
	s_cbranch_scc0 .LBB0_340
	v_readlane_b32 s2, v255, 27
	s_cmp_lt_i32 s2, 3
	s_movk_i32 s2, 0x480
	s_cselect_b32 s8, s2, 0x400
	v_readlane_b32 s3, v255, 28
	s_cmp_lt_i32 s83, s8
	s_cselect_b64 s[2:3], -1, 0
	v_cndmask_b32_e64 v0, 0, 1, s[2:3]
	s_mov_b64 s[4:5], -1
	s_and_b64 vcc, exec, s[0:1]
	v_cmp_ne_u32_e64 s[2:3], 1, v0
	s_cbranch_vccnz .LBB0_318
	s_and_b64 vcc, exec, s[2:3]
	s_cbranch_vccnz .LBB0_317
	v_and_b32_e32 v208, 31, v174
	v_bfe_u32 v209, v174, 5, 1
	v_lshrrev_b32_e32 v210, 6, v174
	v_lshrrev_b32_e32 v211, 3, v174
	v_and_b32_e32 v212, 7, v174
	v_mov_b32_e32 v213, s23
	s_movk_i32 s15, 0xd0
	v_mad_u32_u24 v243, v208, s15, v213
	v_lshl_add_u32 v243, v209, 4, v243
	v_mad_u32_u24 v218, v211, s15, v213
	v_lshl_add_u32 v219, v212, 3, v218
	v_add_u32_e32 v219, 0x80, v219
	v_lshl_add_u32 v218, v212, 4, v218
	s_movk_i32 s15, 0xc0
	v_bfe_u32 v214, v174, 2, 2
	v_lshl_add_u32 v214, v209, 2, v214
	v_mad_u32_u24 v220, v214, s15, v213
	v_bfe_u32 v215, v174, 4, 1
	v_and_b32_e32 v216, 3, v174
	v_lshlrev_b32_e32 v215, 5, v215
	v_lshl_add_u32 v215, v216, 3, v215
	v_add_u32_e32 v220, v220, v215
	v_add_u32_e32 v220, 0x6800, v220
	v_mad_u32_u24 v221, v211, s15, v213
	v_lshl_add_u32 v221, v212, 4, v221
	v_add_u32_e32 v221, 0x6800, v221
	v_lshlrev_b32_e32 v225, 7, v211
	v_lshl_add_u32 v225, v212, 4, v225
	v_lshlrev_b32_e32 v165, 6, v211
	v_lshl_add_u32 v165, v212, 3, v165
	v_lshl_add_u32 v217, v210, 5, v208
	s_movk_i32 s15, 0xc00
	v_mul_u32_u24_e32 v171, s15, v217
	v_lshl_add_u32 v171, v209, 4, v171
	v_lshlrev_b32_e32 v172, 11, v217
	v_lshl_add_u32 v172, v209, 4, v172
	v_mov_b32_e32 v167, 0
	v_and_b32_e32 v214, 15, v174
	v_bfe_u32 v215, v174, 4, 1
	v_cmp_eq_u32_e32 vcc, v214, v215
	v_mov_b32_e32 v216, 0x3f803f80
	s_nop 1
	v_cndmask_b32_e32 v246, 0, v216, vcc
	v_cndmask_b32_e32 v247, 0, v216, vcc
	v_cndmask_b32_e32 v248, 0, v216, vcc
	v_cndmask_b32_e32 v249, 0, v216, vcc
	v_lshlrev_b32_e32 v230, 2, v214
	v_add_u32_e32 v231, 64, v230
	v_readfirstlane_b32 s58, v210
	s_mov_b32 s6, s83
	s_lshr_b32 s58, s58, 2
	s_cmpk_gt_i32 s6, 0x3ff
	s_cbranch_scc0 .Lamla_mainitem_first
	s_add_i32 s21, s6, 0xfffffc00
	s_lshr_b32 s15, s21, 4
	s_and_b32 s18, s21, 15
	s_lshl_b32 s20, s15, 8
	s_add_i32 s20, s20, 0x4000
	s_mov_b32 s7, 0
	s_branch .Lamla_decoded_first

; #define AT_GLOADK(k0) do { kreg = *(const u32x4*)(Kb + (size_t)((k0) + (tid >> 3)) * 64 + (tid & 7) * 8); \
;             if (MLA) preg = *(const u32x2*)(Pb + (size_t)((k0) + (tid >> 3)) * 32 + (tid & 7) * 4); } while (0)
; #define AT_GLOADV(k0) do { vreg = *(const u32x4*)(Vb + (size_t)((k0) + (tid >> 3)) * 64 + (tid & 7) * 8); } while (0)
; #define AT_WRITEK(buf) do { *(LAS u32x4*)(lds + (buf) * KBUF + (tid >> 3) * KSTR + (tid & 7) * 16) = kreg; \
;             if (MLA) *(LAS u32x2*)(lds + (buf) * KBUF + (tid >> 3) * KSTR + 128 + (tid & 7) * 8) = preg; } while (0)
; #define AT_WRITEV(buf) do { *(LAS u32x4*)(lds + 2 * KBUF + (buf) * VBUF + (tid >> 3) * VSTR + (tid & 7) * 16) = vreg; } while (0)
; template <bool MLA>
; DI void attn_phase(const int TID, const int BID, LAS unsigned char* lds, const Params& p, bool need_ctx) {
;     ...
;         f32x16 o0, o1, sa0, sa1, sb0, sb1;
; #pragma unroll
;         for (int j = 0; j < 16; ++j) { o0[j] = 0.f; o1[j] = 0.f; }
;         float mrun = -1e30f, lsum = 0.f;
;         if (wid >= 4) __builtin_amdgcn_s_setprio(1);
;         const int ntile = nk >> 6;
;         AT_GLOADK(0); AT_GLOADV(0); AT_WRITEK(0); AT_WRITEV(0);
;         AT_GLOADK(64); AT_WRITEK(1);
;         __syncthreads();
.Lamla_item:
	s_mov_b32 s52, 0x3000
	s_mov_b32 s53, 0x6000
	s_mov_b32 s54, 0
	v_mov_b64_e32 v[0:1], 0
	v_mov_b64_e32 v[2:3], 0
	v_mov_b64_e32 v[4:5], 0
	v_mov_b64_e32 v[6:7], 0
	v_mov_b64_e32 v[8:9], 0
	v_mov_b64_e32 v[10:11], 0
	v_mov_b64_e32 v[12:13], 0
	v_mov_b64_e32 v[14:15], 0
	v_mov_b64_e32 v[16:17], 0
	v_mov_b64_e32 v[18:19], 0
	v_mov_b64_e32 v[20:21], 0
	v_mov_b64_e32 v[22:23], 0
	v_mov_b64_e32 v[24:25], 0
	v_mov_b64_e32 v[26:27], 0
	v_mov_b64_e32 v[28:29], 0
	v_mov_b64_e32 v[30:31], 0
	v_mov_b32_e32 v162, 0xf149f2ca
	v_mov_b32_e32 v164, 0xf149f2ca
	v_mov_b32_e32 v163, 0x7149f2ca
	v_mov_b64_e32 v[226:227], 0
	v_mov_b64_e32 v[228:229], 0
	s_barrier
	s_waitcnt vmcnt(7)
	ds_write_b128 v218, v[136:139]
	s_waitcnt vmcnt(6)
	ds_write_b64 v219, v[208:209]
	s_waitcnt vmcnt(5)
	ds_write_b128 v218, v[140:143] offset:13312
	s_waitcnt vmcnt(4)
	ds_write_b64 v219, v[210:211] offset:13312
	s_waitcnt vmcnt(3)
	ds_write_b128 v221, v[144:147]
	s_waitcnt lgkmcnt(0)
	s_barrier
	s_cmp_eq_u32 s58, 0
	s_cbranch_scc1 .Lamla_prio
	s_setprio 1

.Lamla_loop:
	ds_read_b128 v[136:139], v243 offset:0
	ds_read_b128 v[140:143], v243 offset:6656
	ds_read_b128 v[144:147], v243 offset:32
	ds_read_b128 v[148:151], v243 offset:6688
	s_waitcnt lgkmcnt(10)
	v_mfma_f32_32x32x16_bf16 v[0:15], v[176:179], v[96:99], v[0:15]
	v_max3_f32 v168, v64, v65, v66
	v_max3_f32 v170, v80, v81, v82
	v_max3_f32 v168, v168, v67, v68
	v_max3_f32 v170, v170, v83, v84
	v_max3_f32 v168, v168, v69, v70
	v_max3_f32 v170, v170, v85, v86
	s_mov_b32 s55, s52
	s_mov_b32 s52, s53
	s_mov_b32 s53, s54
	s_mov_b32 s54, s55
	s_mov_b32 s9, 0
	s_waitcnt lgkmcnt(8)
	v_mfma_f32_32x32x16_bf16 v[16:31], v[180:183], v[96:99], v[16:31]
	v_max3_f32 v168, v168, v71, v72
	v_max3_f32 v170, v170, v87, v88
	v_max3_f32 v168, v168, v73, v74
	v_max3_f32 v170, v170, v89, v90
	v_max3_f32 v168, v168, v75, v76
	v_max3_f32 v170, v170, v91, v92
	global_load_dwordx4 v[152:155], v225, s[2:3]
	global_load_dwordx2 v[160:161], v165, s[10:11]
	global_load_dwordx4 v[156:159], v225, s[4:5]
	s_add_u32 s2, s2, 0x2000
	s_addc_u32 s3, s3, 0
	s_add_u32 s10, s10, 0x1000
	s_addc_u32 s11, s11, 0
	s_add_u32 s4, s4, 0x2000
	s_addc_u32 s5, s5, 0
	v_add_u32_e32 v222, s53, v220
	v_add_u32_e32 v224, s54, v221
	v_mfma_f32_16x16x32_bf16 v[226:229], v[246:249], v[96:99], v[226:229]
	v_max3_f32 v168, v168, v77, v78
	v_max3_f32 v170, v170, v93, v94
	v_max_f32_e32 v168, v168, v79
	v_max_f32_e32 v170, v170, v95
	v_max_f32_e32 v168, v168, v170
	s_waitcnt lgkmcnt(3)
	v_mfma_f32_32x32x16_bf16 v[32:47], v[136:139], v[112:115], 0
	v_mov_b32_e32 v170, v168
	s_nop 1
	v_permlane32_swap_b32_e32 v168, v170
	v_max_f32_e32 v168, v168, v170
	v_mul_f32_e32 v168, 0x3e16c740, v168
	v_cmp_gt_f32_e32 vcc, v168, v164
	s_cbranch_vccz .Lamla_nors_2
	v_max_f32_e32 v170, v162, v168
	v_sub_f32_e32 v166, v162, v170
	v_exp_f32_e32 v166, v166
	v_mov_b32_e32 v162, v170
	v_add_f32_e32 v164, 0x41000000, v170
	v_xor_b32_e32 v163, 0x80000000, v170
	s_mov_b32 s9, 1
.Lamla_nors_2:
	ds_read_b128 v[136:139], v243 offset:64
	ds_read_b64_tr_b16 v[192:193], v223 offset:3072
	ds_read_b64_tr_b16 v[194:195], v223 offset:4608
	s_waitcnt lgkmcnt(5)
	v_mfma_f32_32x32x16_bf16 v[48:63], v[140:143], v[112:115], 0
	v_fmamk_f32 v64, v64, 0x3e16c740, v163
	v_fmamk_f32 v80, v80, 0x3e16c740, v163
	v_exp_f32_e32 v64, v64
	v_exp_f32_e32 v80, v80
	ds_read_b128 v[140:143], v243 offset:6720
	ds_read_b64_tr_b16 v[196:197], v223 offset:3136
	ds_read_b64_tr_b16 v[198:199], v223 offset:4672
	v_mfma_f32_32x32x16_bf16 v[0:15], v[184:187], v[104:107], v[0:15]
	v_fmamk_f32 v65, v65, 0x3e16c740, v163
	v_fmamk_f32 v81, v81, 0x3e16c740, v163
	v_exp_f32_e32 v65, v65
	v_exp_f32_e32 v81, v81
	ds_read_b64_tr_b16 v[200:201], v223 offset:9216
	ds_read_b64_tr_b16 v[202:203], v223 offset:10752
	s_waitcnt lgkmcnt(9)
	v_mfma_f32_32x32x16_bf16 v[32:47], v[144:147], v[116:119], v[32:47]
	v_fmamk_f32 v66, v66, 0x3e16c740, v163
	v_fmamk_f32 v82, v82, 0x3e16c740, v163
	v_exp_f32_e32 v66, v66
	v_exp_f32_e32 v82, v82
	ds_read_b128 v[144:147], v243 offset:96
	ds_read_b64_tr_b16 v[204:205], v223 offset:9280
	ds_read_b64_tr_b16 v[206:207], v223 offset:10816
	v_mfma_f32_32x32x16_bf16 v[16:31], v[188:191], v[104:107], v[16:31]
	v_cvt_pk_bf16_f32 v96, v64, v65
	v_fmamk_f32 v67, v67, 0x3e16c740, v163
	v_fmamk_f32 v83, v83, 0x3e16c740, v163
	v_exp_f32_e32 v67, v67
	s_waitcnt lgkmcnt(11)
	v_mfma_f32_32x32x16_bf16 v[48:63], v[148:151], v[116:119], v[48:63]
	v_exp_f32_e32 v83, v83
	v_fmamk_f32 v68, v68, 0x3e16c740, v163
	v_fmamk_f32 v84, v84, 0x3e16c740, v163
	v_exp_f32_e32 v68, v68
	ds_read_b128 v[148:151], v243 offset:6752
	v_mfma_f32_16x16x32_bf16 v[226:229], v[246:249], v[104:107], v[226:229]
	v_cvt_pk_bf16_f32 v104, v80, v81
	v_exp_f32_e32 v84, v84
	v_cvt_pk_bf16_f32 v97, v66, v67
	v_cvt_pk_bf16_f32 v105, v82, v83
	v_fmamk_f32 v69, v69, 0x3e16c740, v163
	s_waitcnt lgkmcnt(11)
	v_mfma_f32_32x32x16_bf16 v[32:47], v[136:139], v[120:123], v[32:47]
	v_fmamk_f32 v85, v85, 0x3e16c740, v163
	v_exp_f32_e32 v69, v69
	v_exp_f32_e32 v85, v85
	ds_read_b128 v[136:139], v243 offset:128
	s_waitcnt lgkmcnt(9)
	v_mfma_f32_32x32x16_bf16 v[48:63], v[140:143], v[120:123], v[48:63]
	v_fmamk_f32 v70, v70, 0x3e16c740, v163
	v_fmamk_f32 v86, v86, 0x3e16c740, v163
	v_exp_f32_e32 v70, v70
	v_exp_f32_e32 v86, v86
	ds_read_b128 v[140:143], v243 offset:6784
	v_mfma_f32_32x32x16_bf16 v[0:15], v[192:195], v[100:103], v[0:15]
	v_cvt_pk_bf16_f32 v98, v68, v69
	v_cvt_pk_bf16_f32 v106, v84, v85
	v_fmamk_f32 v71, v71, 0x3e16c740, v163
	v_fmamk_f32 v87, v87, 0x3e16c740, v163
	v_exp_f32_e32 v71, v71
	s_waitcnt lgkmcnt(5)
	v_mfma_f32_32x32x16_bf16 v[32:47], v[144:147], v[124:127], v[32:47]
	v_exp_f32_e32 v87, v87
	v_fmamk_f32 v72, v72, 0x3e16c740, v163
	v_fmamk_f32 v88, v88, 0x3e16c740, v163
	v_exp_f32_e32 v72, v72
	ds_read_b128 v[144:147], v243 offset:160
	v_mfma_f32_32x32x16_bf16 v[16:31], v[196:199], v[100:103], v[16:31]
	v_exp_f32_e32 v88, v88
	v_cvt_pk_bf16_f32 v99, v70, v71
	v_cvt_pk_bf16_f32 v107, v86, v87
	v_fmamk_f32 v73, v73, 0x3e16c740, v163
	s_waitcnt vmcnt(5)
	ds_write_b128 v218, v[208:211] offset:13312
	s_waitcnt vmcnt(4)
	ds_write_b64 v219, v[216:217] offset:13312
	s_waitcnt vmcnt(3)
	ds_write_b128 v224, v[212:215]
	s_waitcnt lgkmcnt(6)
	v_mfma_f32_32x32x16_bf16 v[48:63], v[148:151], v[124:127], v[48:63]
	v_fmamk_f32 v89, v89, 0x3e16c740, v163
	v_exp_f32_e32 v73, v73
	v_exp_f32_e32 v89, v89
	ds_read_b128 v[148:151], v243 offset:6816
	v_mfma_f32_16x16x32_bf16 v[226:229], v[246:249], v[100:103], v[226:229]
	v_fmamk_f32 v74, v74, 0x3e16c740, v163
	v_fmamk_f32 v90, v90, 0x3e16c740, v163
	v_exp_f32_e32 v74, v74
	v_exp_f32_e32 v90, v90
	s_waitcnt lgkmcnt(6)
	v_mfma_f32_32x32x16_bf16 v[32:47], v[136:139], v[128:131], v[32:47]
	v_cvt_pk_bf16_f32 v100, v72, v73
	v_fmamk_f32 v75, v75, 0x3e16c740, v163
	v_fmamk_f32 v91, v91, 0x3e16c740, v163
	v_exp_f32_e32 v75, v75
	v_exp_f32_e32 v91, v91
	s_waitcnt lgkmcnt(5)
	v_mfma_f32_32x32x16_bf16 v[48:63], v[140:143], v[128:131], v[48:63]
	v_fmamk_f32 v76, v76, 0x3e16c740, v163
	v_fmamk_f32 v92, v92, 0x3e16c740, v163
	v_exp_f32_e32 v76, v76
	ds_read_b64_tr_b16 v[176:177], v222 offset:0
	ds_read_b64_tr_b16 v[178:179], v222 offset:1536
	v_mfma_f32_32x32x16_bf16 v[0:15], v[200:203], v[108:111], v[0:15]
	v_exp_f32_e32 v92, v92
	v_cvt_pk_bf16_f32 v101, v74, v75
	v_fmamk_f32 v77, v77, 0x3e16c740, v163
	v_fmamk_f32 v93, v93, 0x3e16c740, v163
	v_exp_f32_e32 v77, v77
	ds_read_b64_tr_b16 v[180:181], v222 offset:64
	ds_read_b64_tr_b16 v[182:183], v222 offset:1600
	s_waitcnt lgkmcnt(8)
	v_mfma_f32_32x32x16_bf16 v[32:47], v[144:147], v[132:135], v[32:47]
	v_exp_f32_e32 v93, v93
	v_fmamk_f32 v78, v78, 0x3e16c740, v163
	v_fmamk_f32 v94, v94, 0x3e16c740, v163
	v_exp_f32_e32 v78, v78
	ds_read_b64_tr_b16 v[184:185], v222 offset:6144
	ds_read_b64_tr_b16 v[186:187], v222 offset:7680
	v_mfma_f32_32x32x16_bf16 v[16:31], v[204:207], v[108:111], v[16:31]
	v_exp_f32_e32 v94, v94
	v_cvt_pk_bf16_f32 v102, v76, v77
	v_fmamk_f32 v79, v79, 0x3e16c740, v163
	ds_read_b64_tr_b16 v[188:189], v222 offset:6208
	ds_read_b64_tr_b16 v[190:191], v222 offset:7744
	s_waitcnt lgkmcnt(8)
	v_mfma_f32_32x32x16_bf16 v[48:63], v[148:151], v[132:135], v[48:63]
	v_fmamk_f32 v95, v95, 0x3e16c740, v163
	v_exp_f32_e32 v79, v79
	v_exp_f32_e32 v95, v95
	v_cvt_pk_bf16_f32 v103, v78, v79
	v_mfma_f32_16x16x32_bf16 v[226:229], v[246:249], v[108:111], v[226:229]
	v_cvt_pk_bf16_f32 v108, v88, v89
	v_cvt_pk_bf16_f32 v109, v90, v91
	v_cvt_pk_bf16_f32 v110, v92, v93
	v_cvt_pk_bf16_f32 v111, v94, v95
	s_cmp_lg_u32 s9, 0
	s_cbranch_scc0 .Lamla_noresc_3
	s_nop 15
	v_pk_mul_f32 v[0:1], v[0:1], v[166:167] op_sel_hi:[1,0]
	v_pk_mul_f32 v[2:3], v[2:3], v[166:167] op_sel_hi:[1,0]
	v_pk_mul_f32 v[4:5], v[4:5], v[166:167] op_sel_hi:[1,0]
	v_pk_mul_f32 v[6:7], v[6:7], v[166:167] op_sel_hi:[1,0]
	v_pk_mul_f32 v[8:9], v[8:9], v[166:167] op_sel_hi:[1,0]
	v_pk_mul_f32 v[10:11], v[10:11], v[166:167] op_sel_hi:[1,0]
	v_pk_mul_f32 v[12:13], v[12:13], v[166:167] op_sel_hi:[1,0]
	v_pk_mul_f32 v[14:15], v[14:15], v[166:167] op_sel_hi:[1,0]
	v_pk_mul_f32 v[16:17], v[16:17], v[166:167] op_sel_hi:[1,0]
	v_pk_mul_f32 v[18:19], v[18:19], v[166:167] op_sel_hi:[1,0]
	v_pk_mul_f32 v[20:21], v[20:21], v[166:167] op_sel_hi:[1,0]
	v_pk_mul_f32 v[22:23], v[22:23], v[166:167] op_sel_hi:[1,0]
	v_pk_mul_f32 v[24:25], v[24:25], v[166:167] op_sel_hi:[1,0]
	v_pk_mul_f32 v[26:27], v[26:27], v[166:167] op_sel_hi:[1,0]
	v_pk_mul_f32 v[28:29], v[28:29], v[166:167] op_sel_hi:[1,0]
	v_pk_mul_f32 v[30:31], v[30:31], v[166:167] op_sel_hi:[1,0]
	ds_bpermute_b32 v173, v231, v166
	v_mul_f32_e32 v226, v226, v166
	s_waitcnt lgkmcnt(0)
	v_mul_f32_e32 v227, v227, v173
.Lamla_noresc_3:
	s_barrier
	ds_read_b128 v[136:139], v243 offset:13312
	ds_read_b128 v[140:143], v243 offset:19968
	ds_read_b128 v[144:147], v243 offset:13344
	ds_read_b128 v[148:151], v243 offset:20000
	s_waitcnt lgkmcnt(10)
	v_mfma_f32_32x32x16_bf16 v[0:15], v[176:179], v[96:99], v[0:15]
	v_max3_f32 v168, v32, v33, v34
	v_max3_f32 v170, v48, v49, v50
	v_max3_f32 v168, v168, v35, v36
	v_max3_f32 v170, v170, v51, v52
	v_max3_f32 v168, v168, v37, v38
	v_max3_f32 v170, v170, v53, v54
	s_mov_b32 s55, s52
	s_mov_b32 s52, s53
	s_mov_b32 s53, s54
	s_mov_b32 s54, s55
	s_mov_b32 s9, 0
	s_waitcnt lgkmcnt(8)
	v_mfma_f32_32x32x16_bf16 v[16:31], v[180:183], v[96:99], v[16:31]
	v_max3_f32 v168, v168, v39, v40
	v_max3_f32 v170, v170, v55, v56
	v_max3_f32 v168, v168, v41, v42
	v_max3_f32 v170, v170, v57, v58
	v_max3_f32 v168, v168, v43, v44
	v_max3_f32 v170, v170, v59, v60
	global_load_dwordx4 v[208:211], v225, s[2:3]
	global_load_dwordx2 v[216:217], v165, s[10:11]
	global_load_dwordx4 v[212:215], v225, s[4:5]
	s_add_u32 s2, s2, 0x2000
	s_addc_u32 s3, s3, 0
	s_add_u32 s10, s10, 0x1000
	s_addc_u32 s11, s11, 0
	s_add_u32 s4, s4, 0x2000
	s_addc_u32 s5, s5, 0
	v_add_u32_e32 v223, s53, v220
	v_add_u32_e32 v224, s54, v221
	v_mfma_f32_16x16x32_bf16 v[226:229], v[246:249], v[96:99], v[226:229]
	v_max3_f32 v168, v168, v45, v46
	v_max3_f32 v170, v170, v61, v62
	v_max_f32_e32 v168, v168, v47
	v_max_f32_e32 v170, v170, v63
	v_max_f32_e32 v168, v168, v170
	s_waitcnt lgkmcnt(3)
	v_mfma_f32_32x32x16_bf16 v[64:79], v[136:139], v[112:115], 0
	v_mov_b32_e32 v170, v168
	s_nop 1
	v_permlane32_swap_b32_e32 v168, v170
	v_max_f32_e32 v168, v168, v170
	v_mul_f32_e32 v168, 0x3e16c740, v168
	v_cmp_gt_f32_e32 vcc, v168, v164
	s_cbranch_vccz .Lamla_nors_4
	v_max_f32_e32 v170, v162, v168
	v_sub_f32_e32 v166, v162, v170
	v_exp_f32_e32 v166, v166
	v_mov_b32_e32 v162, v170
	v_add_f32_e32 v164, 0x41000000, v170
	v_xor_b32_e32 v163, 0x80000000, v170
	s_mov_b32 s9, 1
.Lamla_nors_4:
	ds_read_b128 v[136:139], v243 offset:13376
	ds_read_b64_tr_b16 v[192:193], v222 offset:3072
	ds_read_b64_tr_b16 v[194:195], v222 offset:4608
	s_waitcnt lgkmcnt(5)
	v_mfma_f32_32x32x16_bf16 v[80:95], v[140:143], v[112:115], 0
	v_fmamk_f32 v32, v32, 0x3e16c740, v163
	v_fmamk_f32 v48, v48, 0x3e16c740, v163
	v_exp_f32_e32 v32, v32
	v_exp_f32_e32 v48, v48
	ds_read_b128 v[140:143], v243 offset:20032
	ds_read_b64_tr_b16 v[196:197], v222 offset:3136
	ds_read_b64_tr_b16 v[198:199], v222 offset:4672
	v_mfma_f32_32x32x16_bf16 v[0:15], v[184:187], v[104:107], v[0:15]
	v_fmamk_f32 v33, v33, 0x3e16c740, v163
	v_fmamk_f32 v49, v49, 0x3e16c740, v163
	v_exp_f32_e32 v33, v33
	v_exp_f32_e32 v49, v49
	ds_read_b64_tr_b16 v[200:201], v222 offset:9216
	ds_read_b64_tr_b16 v[202:203], v222 offset:10752
	s_waitcnt lgkmcnt(9)
	v_mfma_f32_32x32x16_bf16 v[64:79], v[144:147], v[116:119], v[64:79]
	v_fmamk_f32 v34, v34, 0x3e16c740, v163
	v_fmamk_f32 v50, v50, 0x3e16c740, v163
	v_exp_f32_e32 v34, v34
	v_exp_f32_e32 v50, v50
	ds_read_b128 v[144:147], v243 offset:13408
	ds_read_b64_tr_b16 v[204:205], v222 offset:9280
	ds_read_b64_tr_b16 v[206:207], v222 offset:10816
	v_mfma_f32_32x32x16_bf16 v[16:31], v[188:191], v[104:107], v[16:31]
	v_cvt_pk_bf16_f32 v96, v32, v33
	v_fmamk_f32 v35, v35, 0x3e16c740, v163
	v_fmamk_f32 v51, v51, 0x3e16c740, v163
	v_exp_f32_e32 v35, v35
	s_waitcnt lgkmcnt(11)
	v_mfma_f32_32x32x16_bf16 v[80:95], v[148:151], v[116:119], v[80:95]
	v_exp_f32_e32 v51, v51
	v_fmamk_f32 v36, v36, 0x3e16c740, v163
	v_fmamk_f32 v52, v52, 0x3e16c740, v163
	v_exp_f32_e32 v36, v36
	ds_read_b128 v[148:151], v243 offset:20064
	v_mfma_f32_16x16x32_bf16 v[226:229], v[246:249], v[104:107], v[226:229]
	v_cvt_pk_bf16_f32 v104, v48, v49
	v_exp_f32_e32 v52, v52
	v_cvt_pk_bf16_f32 v97, v34, v35
	v_cvt_pk_bf16_f32 v105, v50, v51
	v_fmamk_f32 v37, v37, 0x3e16c740, v163
	s_waitcnt lgkmcnt(11)
	v_mfma_f32_32x32x16_bf16 v[64:79], v[136:139], v[120:123], v[64:79]
	v_fmamk_f32 v53, v53, 0x3e16c740, v163
	v_exp_f32_e32 v37, v37
	v_exp_f32_e32 v53, v53
	ds_read_b128 v[136:139], v243 offset:13440
	s_waitcnt lgkmcnt(9)
	v_mfma_f32_32x32x16_bf16 v[80:95], v[140:143], v[120:123], v[80:95]
	v_fmamk_f32 v38, v38, 0x3e16c740, v163
	v_fmamk_f32 v54, v54, 0x3e16c740, v163
	v_exp_f32_e32 v38, v38
	v_exp_f32_e32 v54, v54
	ds_read_b128 v[140:143], v243 offset:20096
	v_mfma_f32_32x32x16_bf16 v[0:15], v[192:195], v[100:103], v[0:15]
	v_cvt_pk_bf16_f32 v98, v36, v37
	v_cvt_pk_bf16_f32 v106, v52, v53
	v_fmamk_f32 v39, v39, 0x3e16c740, v163
	v_fmamk_f32 v55, v55, 0x3e16c740, v163
	v_exp_f32_e32 v39, v39
	s_waitcnt lgkmcnt(5)
	v_mfma_f32_32x32x16_bf16 v[64:79], v[144:147], v[124:127], v[64:79]
	v_exp_f32_e32 v55, v55
	v_fmamk_f32 v40, v40, 0x3e16c740, v163
	v_fmamk_f32 v56, v56, 0x3e16c740, v163
	v_exp_f32_e32 v40, v40
	ds_read_b128 v[144:147], v243 offset:13472
	v_mfma_f32_32x32x16_bf16 v[16:31], v[196:199], v[100:103], v[16:31]
	v_exp_f32_e32 v56, v56
	v_cvt_pk_bf16_f32 v99, v38, v39
	v_cvt_pk_bf16_f32 v107, v54, v55
	v_fmamk_f32 v41, v41, 0x3e16c740, v163
	s_waitcnt vmcnt(5)
	ds_write_b128 v218, v[152:155]
	s_waitcnt vmcnt(4)
	ds_write_b64 v219, v[160:161]
	s_waitcnt vmcnt(3)
	ds_write_b128 v224, v[156:159]
	s_waitcnt lgkmcnt(6)
	v_mfma_f32_32x32x16_bf16 v[80:95], v[148:151], v[124:127], v[80:95]
	v_fmamk_f32 v57, v57, 0x3e16c740, v163
	v_exp_f32_e32 v41, v41
	v_exp_f32_e32 v57, v57
	ds_read_b128 v[148:151], v243 offset:20128
	v_mfma_f32_16x16x32_bf16 v[226:229], v[246:249], v[100:103], v[226:229]
	v_fmamk_f32 v42, v42, 0x3e16c740, v163
	v_fmamk_f32 v58, v58, 0x3e16c740, v163
	v_exp_f32_e32 v42, v42
	v_exp_f32_e32 v58, v58
	s_waitcnt lgkmcnt(6)
	v_mfma_f32_32x32x16_bf16 v[64:79], v[136:139], v[128:131], v[64:79]
	v_cvt_pk_bf16_f32 v100, v40, v41
	v_fmamk_f32 v43, v43, 0x3e16c740, v163
	v_fmamk_f32 v59, v59, 0x3e16c740, v163
	v_exp_f32_e32 v43, v43
	v_exp_f32_e32 v59, v59
	s_waitcnt lgkmcnt(5)
	v_mfma_f32_32x32x16_bf16 v[80:95], v[140:143], v[128:131], v[80:95]
	v_fmamk_f32 v44, v44, 0x3e16c740, v163
	v_fmamk_f32 v60, v60, 0x3e16c740, v163
	v_exp_f32_e32 v44, v44
	ds_read_b64_tr_b16 v[176:177], v223 offset:0
	ds_read_b64_tr_b16 v[178:179], v223 offset:1536
	v_mfma_f32_32x32x16_bf16 v[0:15], v[200:203], v[108:111], v[0:15]
	v_exp_f32_e32 v60, v60
	v_cvt_pk_bf16_f32 v101, v42, v43
	v_fmamk_f32 v45, v45, 0x3e16c740, v163
	v_fmamk_f32 v61, v61, 0x3e16c740, v163
	v_exp_f32_e32 v45, v45
	ds_read_b64_tr_b16 v[180:181], v223 offset:64
	ds_read_b64_tr_b16 v[182:183], v223 offset:1600
	s_waitcnt lgkmcnt(8)
	v_mfma_f32_32x32x16_bf16 v[64:79], v[144:147], v[132:135], v[64:79]
	v_exp_f32_e32 v61, v61
	v_fmamk_f32 v46, v46, 0x3e16c740, v163
	v_fmamk_f32 v62, v62, 0x3e16c740, v163
	v_exp_f32_e32 v46, v46
	ds_read_b64_tr_b16 v[184:185], v223 offset:6144
	ds_read_b64_tr_b16 v[186:187], v223 offset:7680
	v_mfma_f32_32x32x16_bf16 v[16:31], v[204:207], v[108:111], v[16:31]
	v_exp_f32_e32 v62, v62
	v_cvt_pk_bf16_f32 v102, v44, v45
	v_fmamk_f32 v47, v47, 0x3e16c740, v163
	ds_read_b64_tr_b16 v[188:189], v223 offset:6208
	ds_read_b64_tr_b16 v[190:191], v223 offset:7744
	s_waitcnt lgkmcnt(8)
	v_mfma_f32_32x32x16_bf16 v[80:95], v[148:151], v[132:135], v[80:95]
	v_fmamk_f32 v63, v63, 0x3e16c740, v163
	v_exp_f32_e32 v47, v47
	v_exp_f32_e32 v63, v63
	v_cvt_pk_bf16_f32 v103, v46, v47
	v_mfma_f32_16x16x32_bf16 v[226:229], v[246:249], v[108:111], v[226:229]
	v_cvt_pk_bf16_f32 v108, v56, v57
	v_cvt_pk_bf16_f32 v109, v58, v59
	v_cvt_pk_bf16_f32 v110, v60, v61
	v_cvt_pk_bf16_f32 v111, v62, v63
	s_cmp_lg_u32 s9, 0
	s_cbranch_scc0 .Lamla_noresc_5
	s_nop 15
	v_pk_mul_f32 v[0:1], v[0:1], v[166:167] op_sel_hi:[1,0]
	v_pk_mul_f32 v[2:3], v[2:3], v[166:167] op_sel_hi:[1,0]
	v_pk_mul_f32 v[4:5], v[4:5], v[166:167] op_sel_hi:[1,0]
	v_pk_mul_f32 v[6:7], v[6:7], v[166:167] op_sel_hi:[1,0]
	v_pk_mul_f32 v[8:9], v[8:9], v[166:167] op_sel_hi:[1,0]
	v_pk_mul_f32 v[10:11], v[10:11], v[166:167] op_sel_hi:[1,0]
	v_pk_mul_f32 v[12:13], v[12:13], v[166:167] op_sel_hi:[1,0]
	v_pk_mul_f32 v[14:15], v[14:15], v[166:167] op_sel_hi:[1,0]
	v_pk_mul_f32 v[16:17], v[16:17], v[166:167] op_sel_hi:[1,0]
	v_pk_mul_f32 v[18:19], v[18:19], v[166:167] op_sel_hi:[1,0]
	v_pk_mul_f32 v[20:21], v[20:21], v[166:167] op_sel_hi:[1,0]
	v_pk_mul_f32 v[22:23], v[22:23], v[166:167] op_sel_hi:[1,0]
	v_pk_mul_f32 v[24:25], v[24:25], v[166:167] op_sel_hi:[1,0]
	v_pk_mul_f32 v[26:27], v[26:27], v[166:167] op_sel_hi:[1,0]
	v_pk_mul_f32 v[28:29], v[28:29], v[166:167] op_sel_hi:[1,0]
	v_pk_mul_f32 v[30:31], v[30:31], v[166:167] op_sel_hi:[1,0]
	ds_bpermute_b32 v173, v231, v166
	v_mul_f32_e32 v226, v226, v166
	s_waitcnt lgkmcnt(0)
	v_mul_f32_e32 v227, v227, v173

.Lamla_tail:
	ds_read_b128 v[136:139], v243 offset:0
	ds_read_b128 v[140:143], v243 offset:6656
	ds_read_b128 v[144:147], v243 offset:32
	ds_read_b128 v[148:151], v243 offset:6688
	s_waitcnt lgkmcnt(10)
	v_mfma_f32_32x32x16_bf16 v[0:15], v[176:179], v[96:99], v[0:15]
	v_max3_f32 v168, v64, v65, v66
	v_max3_f32 v170, v80, v81, v82
	v_max3_f32 v168, v168, v67, v68
	v_max3_f32 v170, v170, v83, v84
	v_max3_f32 v168, v168, v69, v70
	v_max3_f32 v170, v170, v85, v86
	s_mov_b32 s55, s52
	s_mov_b32 s52, s53
	s_mov_b32 s53, s54
	s_mov_b32 s54, s55
	s_mov_b32 s9, 0
	s_waitcnt lgkmcnt(8)
	v_mfma_f32_32x32x16_bf16 v[16:31], v[180:183], v[96:99], v[16:31]
	v_max3_f32 v168, v168, v71, v72
	v_max3_f32 v170, v170, v87, v88
	v_max3_f32 v168, v168, v73, v74
	v_max3_f32 v170, v170, v89, v90
	v_max3_f32 v168, v168, v75, v76
	v_max3_f32 v170, v170, v91, v92
	global_load_dwordx4 v[156:159], v225, s[4:5]
	s_add_u32 s4, s4, 0x2000
	s_addc_u32 s5, s5, 0
	v_add_u32_e32 v222, s53, v220
	v_add_u32_e32 v224, s54, v221
	v_mfma_f32_16x16x32_bf16 v[226:229], v[246:249], v[96:99], v[226:229]
	v_max3_f32 v168, v168, v77, v78
	v_max3_f32 v170, v170, v93, v94
	v_max_f32_e32 v168, v168, v79
	v_max_f32_e32 v170, v170, v95
	v_max_f32_e32 v168, v168, v170
	s_waitcnt lgkmcnt(3)
	v_mfma_f32_32x32x16_bf16 v[32:47], v[136:139], v[112:115], 0
	v_mov_b32_e32 v170, v168
	s_nop 1
	v_permlane32_swap_b32_e32 v168, v170
	v_max_f32_e32 v168, v168, v170
	v_mul_f32_e32 v168, 0x3e16c740, v168
	v_cmp_gt_f32_e32 vcc, v168, v164
	s_cbranch_vccz .Lamla_nors_6
	v_max_f32_e32 v170, v162, v168
	v_sub_f32_e32 v166, v162, v170
	v_exp_f32_e32 v166, v166
	v_mov_b32_e32 v162, v170
	v_add_f32_e32 v164, 0x41000000, v170
	v_xor_b32_e32 v163, 0x80000000, v170
	s_mov_b32 s9, 1
.Lamla_nors_6:
	ds_read_b128 v[136:139], v243 offset:64
	ds_read_b64_tr_b16 v[192:193], v223 offset:3072
	ds_read_b64_tr_b16 v[194:195], v223 offset:4608
	s_waitcnt lgkmcnt(5)
	v_mfma_f32_32x32x16_bf16 v[48:63], v[140:143], v[112:115], 0
	v_fmamk_f32 v64, v64, 0x3e16c740, v163
	v_fmamk_f32 v80, v80, 0x3e16c740, v163
	v_exp_f32_e32 v64, v64
	v_exp_f32_e32 v80, v80
	ds_read_b128 v[140:143], v243 offset:6720
	ds_read_b64_tr_b16 v[196:197], v223 offset:3136
	ds_read_b64_tr_b16 v[198:199], v223 offset:4672
	v_mfma_f32_32x32x16_bf16 v[0:15], v[184:187], v[104:107], v[0:15]
	v_fmamk_f32 v65, v65, 0x3e16c740, v163
	v_fmamk_f32 v81, v81, 0x3e16c740, v163
	v_exp_f32_e32 v65, v65
	v_exp_f32_e32 v81, v81
	ds_read_b64_tr_b16 v[200:201], v223 offset:9216
	ds_read_b64_tr_b16 v[202:203], v223 offset:10752
	s_waitcnt lgkmcnt(9)
	v_mfma_f32_32x32x16_bf16 v[32:47], v[144:147], v[116:119], v[32:47]
	v_fmamk_f32 v66, v66, 0x3e16c740, v163
	v_fmamk_f32 v82, v82, 0x3e16c740, v163
	v_exp_f32_e32 v66, v66
	v_exp_f32_e32 v82, v82
	ds_read_b128 v[144:147], v243 offset:96
	ds_read_b64_tr_b16 v[204:205], v223 offset:9280
	ds_read_b64_tr_b16 v[206:207], v223 offset:10816
	v_mfma_f32_32x32x16_bf16 v[16:31], v[188:191], v[104:107], v[16:31]
	v_cvt_pk_bf16_f32 v96, v64, v65
	v_fmamk_f32 v67, v67, 0x3e16c740, v163
	v_fmamk_f32 v83, v83, 0x3e16c740, v163
	v_exp_f32_e32 v67, v67
	s_waitcnt lgkmcnt(11)
	v_mfma_f32_32x32x16_bf16 v[48:63], v[148:151], v[116:119], v[48:63]
	v_exp_f32_e32 v83, v83
	v_fmamk_f32 v68, v68, 0x3e16c740, v163
	v_fmamk_f32 v84, v84, 0x3e16c740, v163
	v_exp_f32_e32 v68, v68
	ds_read_b128 v[148:151], v243 offset:6752
	v_mfma_f32_16x16x32_bf16 v[226:229], v[246:249], v[104:107], v[226:229]
	v_cvt_pk_bf16_f32 v104, v80, v81
	v_exp_f32_e32 v84, v84
	v_cvt_pk_bf16_f32 v97, v66, v67
	v_cvt_pk_bf16_f32 v105, v82, v83
	v_fmamk_f32 v69, v69, 0x3e16c740, v163
	s_waitcnt lgkmcnt(11)
	v_mfma_f32_32x32x16_bf16 v[32:47], v[136:139], v[120:123], v[32:47]
	v_fmamk_f32 v85, v85, 0x3e16c740, v163
	v_exp_f32_e32 v69, v69
	v_exp_f32_e32 v85, v85
	ds_read_b128 v[136:139], v243 offset:128
	s_waitcnt lgkmcnt(9)
	v_mfma_f32_32x32x16_bf16 v[48:63], v[140:143], v[120:123], v[48:63]
	v_fmamk_f32 v70, v70, 0x3e16c740, v163
	v_fmamk_f32 v86, v86, 0x3e16c740, v163
	v_exp_f32_e32 v70, v70
	v_exp_f32_e32 v86, v86
	ds_read_b128 v[140:143], v243 offset:6784
	v_mfma_f32_32x32x16_bf16 v[0:15], v[192:195], v[100:103], v[0:15]
	v_cvt_pk_bf16_f32 v98, v68, v69
	v_cvt_pk_bf16_f32 v106, v84, v85
	v_fmamk_f32 v71, v71, 0x3e16c740, v163
	v_fmamk_f32 v87, v87, 0x3e16c740, v163
	v_exp_f32_e32 v71, v71
	s_waitcnt lgkmcnt(5)
	v_mfma_f32_32x32x16_bf16 v[32:47], v[144:147], v[124:127], v[32:47]
	v_exp_f32_e32 v87, v87
	v_fmamk_f32 v72, v72, 0x3e16c740, v163
	v_fmamk_f32 v88, v88, 0x3e16c740, v163
	v_exp_f32_e32 v72, v72
	ds_read_b128 v[144:147], v243 offset:160
	v_mfma_f32_32x32x16_bf16 v[16:31], v[196:199], v[100:103], v[16:31]
	v_exp_f32_e32 v88, v88
	v_cvt_pk_bf16_f32 v99, v70, v71
	v_cvt_pk_bf16_f32 v107, v86, v87
	v_fmamk_f32 v73, v73, 0x3e16c740, v163
	s_waitcnt vmcnt(3)
	ds_write_b128 v218, v[208:211] offset:13312
	s_waitcnt vmcnt(2)
	ds_write_b64 v219, v[216:217] offset:13312
	s_waitcnt vmcnt(1)
	ds_write_b128 v224, v[212:215]
	s_waitcnt lgkmcnt(6)
	v_mfma_f32_32x32x16_bf16 v[48:63], v[148:151], v[124:127], v[48:63]
	v_fmamk_f32 v89, v89, 0x3e16c740, v163
	v_exp_f32_e32 v73, v73
	v_exp_f32_e32 v89, v89
	ds_read_b128 v[148:151], v243 offset:6816
	v_mfma_f32_16x16x32_bf16 v[226:229], v[246:249], v[100:103], v[226:229]
	v_fmamk_f32 v74, v74, 0x3e16c740, v163
	v_fmamk_f32 v90, v90, 0x3e16c740, v163
	v_exp_f32_e32 v74, v74
	v_exp_f32_e32 v90, v90
	s_waitcnt lgkmcnt(6)
	v_mfma_f32_32x32x16_bf16 v[32:47], v[136:139], v[128:131], v[32:47]
	v_cvt_pk_bf16_f32 v100, v72, v73
	v_fmamk_f32 v75, v75, 0x3e16c740, v163
	v_fmamk_f32 v91, v91, 0x3e16c740, v163
	v_exp_f32_e32 v75, v75
	v_exp_f32_e32 v91, v91
	s_waitcnt lgkmcnt(5)
	v_mfma_f32_32x32x16_bf16 v[48:63], v[140:143], v[128:131], v[48:63]
	v_fmamk_f32 v76, v76, 0x3e16c740, v163
	v_fmamk_f32 v92, v92, 0x3e16c740, v163
	v_exp_f32_e32 v76, v76
	ds_read_b64_tr_b16 v[176:177], v222 offset:0
	ds_read_b64_tr_b16 v[178:179], v222 offset:1536
	v_mfma_f32_32x32x16_bf16 v[0:15], v[200:203], v[108:111], v[0:15]
	v_exp_f32_e32 v92, v92
	v_cvt_pk_bf16_f32 v101, v74, v75
	v_fmamk_f32 v77, v77, 0x3e16c740, v163
	v_fmamk_f32 v93, v93, 0x3e16c740, v163
	v_exp_f32_e32 v77, v77
	ds_read_b64_tr_b16 v[180:181], v222 offset:64
	ds_read_b64_tr_b16 v[182:183], v222 offset:1600
	s_waitcnt lgkmcnt(8)
	v_mfma_f32_32x32x16_bf16 v[32:47], v[144:147], v[132:135], v[32:47]
	v_exp_f32_e32 v93, v93
	v_fmamk_f32 v78, v78, 0x3e16c740, v163
	v_fmamk_f32 v94, v94, 0x3e16c740, v163
	v_exp_f32_e32 v78, v78
	ds_read_b64_tr_b16 v[184:185], v222 offset:6144
	ds_read_b64_tr_b16 v[186:187], v222 offset:7680
	v_mfma_f32_32x32x16_bf16 v[16:31], v[204:207], v[108:111], v[16:31]
	v_exp_f32_e32 v94, v94
	v_cvt_pk_bf16_f32 v102, v76, v77
	v_fmamk_f32 v79, v79, 0x3e16c740, v163
	ds_read_b64_tr_b16 v[188:189], v222 offset:6208
	ds_read_b64_tr_b16 v[190:191], v222 offset:7744
	s_waitcnt lgkmcnt(8)
	v_mfma_f32_32x32x16_bf16 v[48:63], v[148:151], v[132:135], v[48:63]
	v_fmamk_f32 v95, v95, 0x3e16c740, v163
	v_exp_f32_e32 v79, v79
	v_exp_f32_e32 v95, v95
	v_cvt_pk_bf16_f32 v103, v78, v79
	v_mfma_f32_16x16x32_bf16 v[226:229], v[246:249], v[108:111], v[226:229]
	v_cvt_pk_bf16_f32 v108, v88, v89
	v_cvt_pk_bf16_f32 v109, v90, v91
	v_cvt_pk_bf16_f32 v110, v92, v93
	v_cvt_pk_bf16_f32 v111, v94, v95
	s_cmp_lg_u32 s9, 0
	s_cbranch_scc0 .Lamla_noresc_7
	s_nop 15
	v_pk_mul_f32 v[0:1], v[0:1], v[166:167] op_sel_hi:[1,0]
	v_pk_mul_f32 v[2:3], v[2:3], v[166:167] op_sel_hi:[1,0]
	v_pk_mul_f32 v[4:5], v[4:5], v[166:167] op_sel_hi:[1,0]
	v_pk_mul_f32 v[6:7], v[6:7], v[166:167] op_sel_hi:[1,0]
	v_pk_mul_f32 v[8:9], v[8:9], v[166:167] op_sel_hi:[1,0]
	v_pk_mul_f32 v[10:11], v[10:11], v[166:167] op_sel_hi:[1,0]
	v_pk_mul_f32 v[12:13], v[12:13], v[166:167] op_sel_hi:[1,0]
	v_pk_mul_f32 v[14:15], v[14:15], v[166:167] op_sel_hi:[1,0]
	v_pk_mul_f32 v[16:17], v[16:17], v[166:167] op_sel_hi:[1,0]
	v_pk_mul_f32 v[18:19], v[18:19], v[166:167] op_sel_hi:[1,0]
	v_pk_mul_f32 v[20:21], v[20:21], v[166:167] op_sel_hi:[1,0]
	v_pk_mul_f32 v[22:23], v[22:23], v[166:167] op_sel_hi:[1,0]
	v_pk_mul_f32 v[24:25], v[24:25], v[166:167] op_sel_hi:[1,0]
	v_pk_mul_f32 v[26:27], v[26:27], v[166:167] op_sel_hi:[1,0]
	v_pk_mul_f32 v[28:29], v[28:29], v[166:167] op_sel_hi:[1,0]
	v_pk_mul_f32 v[30:31], v[30:31], v[166:167] op_sel_hi:[1,0]
	ds_bpermute_b32 v173, v231, v166
	v_mul_f32_e32 v226, v226, v166
	s_waitcnt lgkmcnt(0)
	v_mul_f32_e32 v227, v227, v173
.Lamla_noresc_7:
	s_barrier
	ds_read_b128 v[136:139], v243 offset:13312
	ds_read_b128 v[140:143], v243 offset:19968
	ds_read_b128 v[144:147], v243 offset:13344
	ds_read_b128 v[148:151], v243 offset:20000
	s_waitcnt lgkmcnt(10)
	v_mfma_f32_32x32x16_bf16 v[0:15], v[176:179], v[96:99], v[0:15]
	v_max3_f32 v168, v32, v33, v34
	v_max3_f32 v170, v48, v49, v50
	v_max3_f32 v168, v168, v35, v36
	v_max3_f32 v170, v170, v51, v52
	v_max3_f32 v168, v168, v37, v38
	v_max3_f32 v170, v170, v53, v54
	s_mov_b32 s55, s52
	s_mov_b32 s52, s53
	s_mov_b32 s53, s54
	s_mov_b32 s54, s55
	s_mov_b32 s9, 0
	s_waitcnt lgkmcnt(8)
	v_mfma_f32_32x32x16_bf16 v[16:31], v[180:183], v[96:99], v[16:31]
	v_max3_f32 v168, v168, v39, v40
	v_max3_f32 v170, v170, v55, v56
	v_max3_f32 v168, v168, v41, v42
	v_max3_f32 v170, v170, v57, v58
	v_max3_f32 v168, v168, v43, v44
	v_max3_f32 v170, v170, v59, v60
	v_add_u32_e32 v223, s53, v220
	v_add_u32_e32 v224, s54, v221
	v_mfma_f32_16x16x32_bf16 v[226:229], v[246:249], v[96:99], v[226:229]
	v_max3_f32 v168, v168, v45, v46
	v_max3_f32 v170, v170, v61, v62
	v_max_f32_e32 v168, v168, v47
	v_max_f32_e32 v170, v170, v63
	v_max_f32_e32 v168, v168, v170
	s_waitcnt lgkmcnt(3)
	v_mfma_f32_32x32x16_bf16 v[64:79], v[136:139], v[112:115], 0
	v_mov_b32_e32 v170, v168
	s_nop 1
	v_permlane32_swap_b32_e32 v168, v170
	v_max_f32_e32 v168, v168, v170
	v_mul_f32_e32 v168, 0x3e16c740, v168
	v_cmp_gt_f32_e32 vcc, v168, v164
	s_cbranch_vccz .Lamla_nors_8
	v_max_f32_e32 v170, v162, v168
	v_sub_f32_e32 v166, v162, v170
	v_exp_f32_e32 v166, v166
	v_mov_b32_e32 v162, v170
	v_add_f32_e32 v164, 0x41000000, v170
	v_xor_b32_e32 v163, 0x80000000, v170
	s_mov_b32 s9, 1
.Lamla_nors_8:
	ds_read_b128 v[136:139], v243 offset:13376
	ds_read_b64_tr_b16 v[192:193], v222 offset:3072
	ds_read_b64_tr_b16 v[194:195], v222 offset:4608
	s_waitcnt lgkmcnt(5)
	v_mfma_f32_32x32x16_bf16 v[80:95], v[140:143], v[112:115], 0
	v_fmamk_f32 v32, v32, 0x3e16c740, v163
	v_fmamk_f32 v48, v48, 0x3e16c740, v163
	v_exp_f32_e32 v32, v32
	v_exp_f32_e32 v48, v48
	ds_read_b128 v[140:143], v243 offset:20032
	ds_read_b64_tr_b16 v[196:197], v222 offset:3136
	ds_read_b64_tr_b16 v[198:199], v222 offset:4672
	v_mfma_f32_32x32x16_bf16 v[0:15], v[184:187], v[104:107], v[0:15]
	v_fmamk_f32 v33, v33, 0x3e16c740, v163
	v_fmamk_f32 v49, v49, 0x3e16c740, v163
	v_exp_f32_e32 v33, v33
	v_exp_f32_e32 v49, v49
	ds_read_b64_tr_b16 v[200:201], v222 offset:9216
	ds_read_b64_tr_b16 v[202:203], v222 offset:10752
	s_waitcnt lgkmcnt(9)
	v_mfma_f32_32x32x16_bf16 v[64:79], v[144:147], v[116:119], v[64:79]
	v_fmamk_f32 v34, v34, 0x3e16c740, v163
	v_fmamk_f32 v50, v50, 0x3e16c740, v163
	v_exp_f32_e32 v34, v34
	v_exp_f32_e32 v50, v50
	ds_read_b128 v[144:147], v243 offset:13408
	ds_read_b64_tr_b16 v[204:205], v222 offset:9280
	ds_read_b64_tr_b16 v[206:207], v222 offset:10816
	v_mfma_f32_32x32x16_bf16 v[16:31], v[188:191], v[104:107], v[16:31]
	v_cvt_pk_bf16_f32 v96, v32, v33
	v_fmamk_f32 v35, v35, 0x3e16c740, v163
	v_fmamk_f32 v51, v51, 0x3e16c740, v163
	v_exp_f32_e32 v35, v35
	s_waitcnt lgkmcnt(11)
	v_mfma_f32_32x32x16_bf16 v[80:95], v[148:151], v[116:119], v[80:95]
	v_exp_f32_e32 v51, v51
	v_fmamk_f32 v36, v36, 0x3e16c740, v163
	v_fmamk_f32 v52, v52, 0x3e16c740, v163
	v_exp_f32_e32 v36, v36
	ds_read_b128 v[148:151], v243 offset:20064
	v_mfma_f32_16x16x32_bf16 v[226:229], v[246:249], v[104:107], v[226:229]
	v_cvt_pk_bf16_f32 v104, v48, v49
	v_exp_f32_e32 v52, v52
	v_cvt_pk_bf16_f32 v97, v34, v35
	v_cvt_pk_bf16_f32 v105, v50, v51
	v_fmamk_f32 v37, v37, 0x3e16c740, v163
	s_waitcnt lgkmcnt(11)
	v_mfma_f32_32x32x16_bf16 v[64:79], v[136:139], v[120:123], v[64:79]
	v_fmamk_f32 v53, v53, 0x3e16c740, v163
	v_exp_f32_e32 v37, v37
	v_exp_f32_e32 v53, v53
	ds_read_b128 v[136:139], v243 offset:13440
	s_waitcnt lgkmcnt(9)
	v_mfma_f32_32x32x16_bf16 v[80:95], v[140:143], v[120:123], v[80:95]
	v_fmamk_f32 v38, v38, 0x3e16c740, v163
	v_fmamk_f32 v54, v54, 0x3e16c740, v163
	v_exp_f32_e32 v38, v38
	v_exp_f32_e32 v54, v54
	ds_read_b128 v[140:143], v243 offset:20096
	v_mfma_f32_32x32x16_bf16 v[0:15], v[192:195], v[100:103], v[0:15]
	v_cvt_pk_bf16_f32 v98, v36, v37
	v_cvt_pk_bf16_f32 v106, v52, v53
	v_fmamk_f32 v39, v39, 0x3e16c740, v163
	v_fmamk_f32 v55, v55, 0x3e16c740, v163
	v_exp_f32_e32 v39, v39
	s_waitcnt lgkmcnt(5)
	v_mfma_f32_32x32x16_bf16 v[64:79], v[144:147], v[124:127], v[64:79]
	v_exp_f32_e32 v55, v55
	v_fmamk_f32 v40, v40, 0x3e16c740, v163
	v_fmamk_f32 v56, v56, 0x3e16c740, v163
	v_exp_f32_e32 v40, v40
	ds_read_b128 v[144:147], v243 offset:13472
	v_mfma_f32_32x32x16_bf16 v[16:31], v[196:199], v[100:103], v[16:31]
	v_exp_f32_e32 v56, v56
	v_cvt_pk_bf16_f32 v99, v38, v39
	v_cvt_pk_bf16_f32 v107, v54, v55
	v_fmamk_f32 v41, v41, 0x3e16c740, v163
	s_waitcnt vmcnt(0)
	ds_write_b128 v224, v[156:159]
	s_waitcnt lgkmcnt(4)
	v_mfma_f32_32x32x16_bf16 v[80:95], v[148:151], v[124:127], v[80:95]
	v_fmamk_f32 v57, v57, 0x3e16c740, v163
	v_exp_f32_e32 v41, v41
	v_exp_f32_e32 v57, v57
	ds_read_b128 v[148:151], v243 offset:20128
	v_mfma_f32_16x16x32_bf16 v[226:229], v[246:249], v[100:103], v[226:229]
	v_fmamk_f32 v42, v42, 0x3e16c740, v163
	v_fmamk_f32 v58, v58, 0x3e16c740, v163
	v_exp_f32_e32 v42, v42
	v_exp_f32_e32 v58, v58
	s_waitcnt lgkmcnt(4)
	v_mfma_f32_32x32x16_bf16 v[64:79], v[136:139], v[128:131], v[64:79]
	v_cvt_pk_bf16_f32 v100, v40, v41
	v_fmamk_f32 v43, v43, 0x3e16c740, v163
	v_fmamk_f32 v59, v59, 0x3e16c740, v163
	v_exp_f32_e32 v43, v43
	v_exp_f32_e32 v59, v59
	s_waitcnt lgkmcnt(3)
	v_mfma_f32_32x32x16_bf16 v[80:95], v[140:143], v[128:131], v[80:95]
	v_fmamk_f32 v44, v44, 0x3e16c740, v163
	v_fmamk_f32 v60, v60, 0x3e16c740, v163
	v_exp_f32_e32 v44, v44
	ds_read_b64_tr_b16 v[176:177], v223 offset:0
	ds_read_b64_tr_b16 v[178:179], v223 offset:1536
	v_mfma_f32_32x32x16_bf16 v[0:15], v[200:203], v[108:111], v[0:15]
	v_exp_f32_e32 v60, v60
	v_cvt_pk_bf16_f32 v101, v42, v43
	v_fmamk_f32 v45, v45, 0x3e16c740, v163
	v_fmamk_f32 v61, v61, 0x3e16c740, v163
	v_exp_f32_e32 v45, v45
	ds_read_b64_tr_b16 v[180:181], v223 offset:64
	ds_read_b64_tr_b16 v[182:183], v223 offset:1600
	s_waitcnt lgkmcnt(6)
	v_mfma_f32_32x32x16_bf16 v[64:79], v[144:147], v[132:135], v[64:79]
	v_exp_f32_e32 v61, v61
	v_fmamk_f32 v46, v46, 0x3e16c740, v163
	v_fmamk_f32 v62, v62, 0x3e16c740, v163
	v_exp_f32_e32 v46, v46
	ds_read_b64_tr_b16 v[184:185], v223 offset:6144
	ds_read_b64_tr_b16 v[186:187], v223 offset:7680
	v_mfma_f32_32x32x16_bf16 v[16:31], v[204:207], v[108:111], v[16:31]
	v_exp_f32_e32 v62, v62
	v_cvt_pk_bf16_f32 v102, v44, v45
	v_fmamk_f32 v47, v47, 0x3e16c740, v163
	ds_read_b64_tr_b16 v[188:189], v223 offset:6208
	ds_read_b64_tr_b16 v[190:191], v223 offset:7744
	s_waitcnt lgkmcnt(8)
	v_mfma_f32_32x32x16_bf16 v[80:95], v[148:151], v[132:135], v[80:95]
	v_fmamk_f32 v63, v63, 0x3e16c740, v163
	v_exp_f32_e32 v47, v47
	v_exp_f32_e32 v63, v63
	v_cvt_pk_bf16_f32 v103, v46, v47
	v_mfma_f32_16x16x32_bf16 v[226:229], v[246:249], v[108:111], v[226:229]
	v_cvt_pk_bf16_f32 v108, v56, v57
	v_cvt_pk_bf16_f32 v109, v58, v59
	v_cvt_pk_bf16_f32 v110, v60, v61
	v_cvt_pk_bf16_f32 v111, v62, v63
	s_cmp_lg_u32 s9, 0
	s_cbranch_scc0 .Lamla_noresc_9
	s_nop 15
	v_pk_mul_f32 v[0:1], v[0:1], v[166:167] op_sel_hi:[1,0]
	v_pk_mul_f32 v[2:3], v[2:3], v[166:167] op_sel_hi:[1,0]
	v_pk_mul_f32 v[4:5], v[4:5], v[166:167] op_sel_hi:[1,0]
	v_pk_mul_f32 v[6:7], v[6:7], v[166:167] op_sel_hi:[1,0]
	v_pk_mul_f32 v[8:9], v[8:9], v[166:167] op_sel_hi:[1,0]
	v_pk_mul_f32 v[10:11], v[10:11], v[166:167] op_sel_hi:[1,0]
	v_pk_mul_f32 v[12:13], v[12:13], v[166:167] op_sel_hi:[1,0]
	v_pk_mul_f32 v[14:15], v[14:15], v[166:167] op_sel_hi:[1,0]
	v_pk_mul_f32 v[16:17], v[16:17], v[166:167] op_sel_hi:[1,0]
	v_pk_mul_f32 v[18:19], v[18:19], v[166:167] op_sel_hi:[1,0]
	v_pk_mul_f32 v[20:21], v[20:21], v[166:167] op_sel_hi:[1,0]
	v_pk_mul_f32 v[22:23], v[22:23], v[166:167] op_sel_hi:[1,0]
	v_pk_mul_f32 v[24:25], v[24:25], v[166:167] op_sel_hi:[1,0]
	v_pk_mul_f32 v[26:27], v[26:27], v[166:167] op_sel_hi:[1,0]
	v_pk_mul_f32 v[28:29], v[28:29], v[166:167] op_sel_hi:[1,0]
	v_pk_mul_f32 v[30:31], v[30:31], v[166:167] op_sel_hi:[1,0]
	ds_bpermute_b32 v173, v231, v166
	v_mul_f32_e32 v226, v226, v166
	s_waitcnt lgkmcnt(0)
	v_mul_f32_e32 v227, v227, v173

.Lamla_nors_10:
	v_add_u32_e32 v222, s53, v220
	v_mfma_f32_16x16x32_bf16 v[226:229], v[246:249], v[96:99], v[226:229]
	v_fmamk_f32 v64, v64, 0x3e16c740, v163
	v_fmamk_f32 v80, v80, 0x3e16c740, v163
	v_exp_f32_e32 v64, v64
	v_exp_f32_e32 v80, v80
	v_fmamk_f32 v65, v65, 0x3e16c740, v163
	v_fmamk_f32 v81, v81, 0x3e16c740, v163
	v_exp_f32_e32 v65, v65
	v_exp_f32_e32 v81, v81
	s_waitcnt lgkmcnt(10)
	v_mfma_f32_32x32x16_bf16 v[0:15], v[184:187], v[104:107], v[0:15]
	v_fmamk_f32 v66, v66, 0x3e16c740, v163
	v_fmamk_f32 v82, v82, 0x3e16c740, v163
	v_exp_f32_e32 v66, v66
	v_exp_f32_e32 v82, v82
	v_cvt_pk_bf16_f32 v96, v64, v65
	v_fmamk_f32 v67, v67, 0x3e16c740, v163
	v_fmamk_f32 v83, v83, 0x3e16c740, v163
	v_exp_f32_e32 v67, v67
	s_waitcnt lgkmcnt(8)
	v_mfma_f32_32x32x16_bf16 v[16:31], v[188:191], v[104:107], v[16:31]
	v_exp_f32_e32 v83, v83
	v_fmamk_f32 v68, v68, 0x3e16c740, v163
	v_fmamk_f32 v84, v84, 0x3e16c740, v163
	v_exp_f32_e32 v68, v68
	v_exp_f32_e32 v84, v84
	v_cvt_pk_bf16_f32 v97, v66, v67
	v_fmamk_f32 v69, v69, 0x3e16c740, v163
	v_fmamk_f32 v85, v85, 0x3e16c740, v163
	v_mfma_f32_16x16x32_bf16 v[226:229], v[246:249], v[104:107], v[226:229]
	v_cvt_pk_bf16_f32 v104, v80, v81
	v_cvt_pk_bf16_f32 v105, v82, v83
	v_exp_f32_e32 v69, v69
	v_exp_f32_e32 v85, v85
	v_fmamk_f32 v70, v70, 0x3e16c740, v163
	v_fmamk_f32 v86, v86, 0x3e16c740, v163
	v_exp_f32_e32 v70, v70
	v_exp_f32_e32 v86, v86
	v_cvt_pk_bf16_f32 v98, v68, v69
	s_waitcnt lgkmcnt(6)
	v_mfma_f32_32x32x16_bf16 v[0:15], v[192:195], v[100:103], v[0:15]
	v_cvt_pk_bf16_f32 v106, v84, v85
	v_fmamk_f32 v71, v71, 0x3e16c740, v163
	v_fmamk_f32 v87, v87, 0x3e16c740, v163
	v_exp_f32_e32 v71, v71
	v_exp_f32_e32 v87, v87
	v_fmamk_f32 v72, v72, 0x3e16c740, v163
	v_fmamk_f32 v88, v88, 0x3e16c740, v163
	v_exp_f32_e32 v72, v72
	ds_read_b64_tr_b16 v[176:177], v222 offset:0
	ds_read_b64_tr_b16 v[178:179], v222 offset:1536
	s_waitcnt lgkmcnt(6)
	v_mfma_f32_32x32x16_bf16 v[16:31], v[196:199], v[100:103], v[16:31]
	v_exp_f32_e32 v88, v88
	v_cvt_pk_bf16_f32 v99, v70, v71
	v_cvt_pk_bf16_f32 v107, v86, v87
	v_fmamk_f32 v73, v73, 0x3e16c740, v163
	v_fmamk_f32 v89, v89, 0x3e16c740, v163
	v_exp_f32_e32 v73, v73
	v_exp_f32_e32 v89, v89
	v_fmamk_f32 v74, v74, 0x3e16c740, v163
	ds_read_b64_tr_b16 v[180:181], v222 offset:64
	ds_read_b64_tr_b16 v[182:183], v222 offset:1600
	v_mfma_f32_16x16x32_bf16 v[226:229], v[246:249], v[100:103], v[226:229]
	v_fmamk_f32 v90, v90, 0x3e16c740, v163
	v_exp_f32_e32 v74, v74
	v_exp_f32_e32 v90, v90
	v_cvt_pk_bf16_f32 v100, v72, v73
	v_fmamk_f32 v75, v75, 0x3e16c740, v163
	v_fmamk_f32 v91, v91, 0x3e16c740, v163
	v_exp_f32_e32 v75, v75
	v_exp_f32_e32 v91, v91
	ds_read_b64_tr_b16 v[184:185], v222 offset:6144
	ds_read_b64_tr_b16 v[186:187], v222 offset:7680
	s_waitcnt lgkmcnt(8)
	v_mfma_f32_32x32x16_bf16 v[0:15], v[200:203], v[108:111], v[0:15]
	v_fmamk_f32 v76, v76, 0x3e16c740, v163
	v_fmamk_f32 v92, v92, 0x3e16c740, v163
	v_exp_f32_e32 v76, v76
	v_exp_f32_e32 v92, v92
	v_cvt_pk_bf16_f32 v101, v74, v75
	v_fmamk_f32 v77, v77, 0x3e16c740, v163
	v_fmamk_f32 v93, v93, 0x3e16c740, v163
	v_exp_f32_e32 v77, v77
	ds_read_b64_tr_b16 v[188:189], v222 offset:6208
	ds_read_b64_tr_b16 v[190:191], v222 offset:7744
	s_waitcnt lgkmcnt(8)
	v_mfma_f32_32x32x16_bf16 v[16:31], v[204:207], v[108:111], v[16:31]
	v_exp_f32_e32 v93, v93
	v_fmamk_f32 v78, v78, 0x3e16c740, v163
	v_fmamk_f32 v94, v94, 0x3e16c740, v163
	v_exp_f32_e32 v78, v78
	v_exp_f32_e32 v94, v94
	v_cvt_pk_bf16_f32 v102, v76, v77
	v_fmamk_f32 v79, v79, 0x3e16c740, v163
	v_fmamk_f32 v95, v95, 0x3e16c740, v163
	v_mfma_f32_16x16x32_bf16 v[226:229], v[246:249], v[108:111], v[226:229]
	v_cvt_pk_bf16_f32 v108, v88, v89
	v_cvt_pk_bf16_f32 v109, v90, v91
	v_cvt_pk_bf16_f32 v110, v92, v93
	v_exp_f32_e32 v79, v79
	v_exp_f32_e32 v95, v95
	v_cvt_pk_bf16_f32 v103, v78, v79
	v_cvt_pk_bf16_f32 v111, v94, v95
	s_cmp_lg_u32 s9, 0
	s_cbranch_scc0 .Lamla_noresc_11
	s_nop 15
	v_pk_mul_f32 v[0:1], v[0:1], v[166:167] op_sel_hi:[1,0]
	v_pk_mul_f32 v[2:3], v[2:3], v[166:167] op_sel_hi:[1,0]
	v_pk_mul_f32 v[4:5], v[4:5], v[166:167] op_sel_hi:[1,0]
	v_pk_mul_f32 v[6:7], v[6:7], v[166:167] op_sel_hi:[1,0]
	v_pk_mul_f32 v[8:9], v[8:9], v[166:167] op_sel_hi:[1,0]
	v_pk_mul_f32 v[10:11], v[10:11], v[166:167] op_sel_hi:[1,0]
	v_pk_mul_f32 v[12:13], v[12:13], v[166:167] op_sel_hi:[1,0]
	v_pk_mul_f32 v[14:15], v[14:15], v[166:167] op_sel_hi:[1,0]
	v_pk_mul_f32 v[16:17], v[16:17], v[166:167] op_sel_hi:[1,0]
	v_pk_mul_f32 v[18:19], v[18:19], v[166:167] op_sel_hi:[1,0]
	v_pk_mul_f32 v[20:21], v[20:21], v[166:167] op_sel_hi:[1,0]
	v_pk_mul_f32 v[22:23], v[22:23], v[166:167] op_sel_hi:[1,0]
	v_pk_mul_f32 v[24:25], v[24:25], v[166:167] op_sel_hi:[1,0]
	v_pk_mul_f32 v[26:27], v[26:27], v[166:167] op_sel_hi:[1,0]
	v_pk_mul_f32 v[28:29], v[28:29], v[166:167] op_sel_hi:[1,0]
	v_pk_mul_f32 v[30:31], v[30:31], v[166:167] op_sel_hi:[1,0]
	ds_bpermute_b32 v173, v231, v166
	v_mul_f32_e32 v226, v226, v166
	s_waitcnt lgkmcnt(0)
	v_mul_f32_e32 v227, v227, v173
; #define AT_STEP(SC0, SC1, SN0, SN1, t, DOK, DOV) do { \
;             if (DOK) AT_GLOADK(((t) + 2) * 64); \
;             if (DOV) { AT_GLOADV(((t) + 1) * 64); AT_QK(SN0, SN1, ((t) + 1) & 1); } \
;             AT_SMPV(SC0, SC1, (t) & 1); \
;             if (DOK) AT_WRITEK((t) & 1); \
;             if (DOV) AT_WRITEV(((t) + 1) & 1); \
;             __syncthreads(); } while (0)
; #define AT_PK4(OX, jg) u32x2 { pk_bf16(OX[4 * (jg)] * inv, OX[4 * (jg) + 1] * inv), pk_bf16(OX[4 * (jg) + 2] * inv, OX[4 * (jg) + 3] * inv) }
; template <bool MLA>
; DI void attn_phase(const int TID, const int BID, LAS unsigned char* lds, const Params& p, bool need_ctx) {
;     ...
;         AT_STEP(sb0, sb1, sa0, sa1, t + 1, false, false);
;         __builtin_amdgcn_s_setprio(0);
;         lsum = xsum32(lsum);
;         const float inv = 1.f / lsum;
;         bf16_t* op = O + (size_t)(row0 + wid * 32 + r) * 1024 + head * 64 + 8 * hh;
;     ...
; #pragma unroll
;         for (int k = 0; k < 2; ++k) {
;             const u32x2 a = AT_PK4(o0, 2 * k), b2 = AT_PK4(o0, 2 * k + 1), c = AT_PK4(o1, 2 * k), d = AT_PK4(o1, 2 * k + 1);
;             const u32x2 s0 = __builtin_amdgcn_permlane32_swap(a[0], b2[0], false, false), s1 = __builtin_amdgcn_permlane32_swap(a[1], b2[1], false, false);
;             const u32x2 t0 = __builtin_amdgcn_permlane32_swap(c[0], d[0], false, false), t1 = __builtin_amdgcn_permlane32_swap(c[1], d[1], false, false);
;             const u32x4 w0 = {s0[0], s1[0], s0[1], s1[1]}, w1 = {t0[0], t1[0], t0[1], t1[1]};
;             *(u32x4*)(op + 16 * k) = w0; *(u32x4*)(op + 32 + 16 * k) = w1;
;         }
.Lamla_noresc_11:
	s_barrier
	ds_read_b64_tr_b16 v[192:193], v222 offset:3072
	ds_read_b64_tr_b16 v[194:195], v222 offset:4608
	ds_read_b64_tr_b16 v[196:197], v222 offset:3136
	ds_read_b64_tr_b16 v[198:199], v222 offset:4672
	s_waitcnt lgkmcnt(10)
	v_mfma_f32_32x32x16_bf16 v[0:15], v[176:179], v[96:99], v[0:15]
	s_mov_b32 s55, s52
	s_mov_b32 s52, s53
	s_mov_b32 s53, s54
	s_mov_b32 s54, s55
	ds_read_b64_tr_b16 v[200:201], v222 offset:9216
	ds_read_b64_tr_b16 v[202:203], v222 offset:10752
	ds_read_b64_tr_b16 v[204:205], v222 offset:9280
	ds_read_b64_tr_b16 v[206:207], v222 offset:10816
	s_waitcnt lgkmcnt(12)
	v_mfma_f32_32x32x16_bf16 v[16:31], v[180:183], v[96:99], v[16:31]
	v_mfma_f32_16x16x32_bf16 v[226:229], v[246:249], v[96:99], v[226:229]
	s_waitcnt lgkmcnt(10)
	v_mfma_f32_32x32x16_bf16 v[0:15], v[184:187], v[104:107], v[0:15]
	s_waitcnt lgkmcnt(8)
	v_mfma_f32_32x32x16_bf16 v[16:31], v[188:191], v[104:107], v[16:31]
	v_mfma_f32_16x16x32_bf16 v[226:229], v[246:249], v[104:107], v[226:229]
	s_waitcnt lgkmcnt(6)
	v_mfma_f32_32x32x16_bf16 v[0:15], v[192:195], v[100:103], v[0:15]
	s_waitcnt lgkmcnt(4)
	v_mfma_f32_32x32x16_bf16 v[16:31], v[196:199], v[100:103], v[16:31]
	v_mfma_f32_16x16x32_bf16 v[226:229], v[246:249], v[100:103], v[226:229]
	s_waitcnt lgkmcnt(2)
	v_mfma_f32_32x32x16_bf16 v[0:15], v[200:203], v[108:111], v[0:15]
	s_waitcnt lgkmcnt(0)
	v_mfma_f32_32x32x16_bf16 v[16:31], v[204:207], v[108:111], v[16:31]
	v_mfma_f32_16x16x32_bf16 v[226:229], v[246:249], v[108:111], v[226:229]
	s_setprio 0
	s_nop 11
	ds_bpermute_b32 v173, v230, v226
	ds_bpermute_b32 v175, v230, v227
	s_mov_b32 s60, 0xffff0000
	s_mov_b32 s61, 0xffff0000
	s_waitcnt lgkmcnt(0)
	v_cndmask_b32_e64 v226, v173, v175, s[60:61]
	v_div_scale_f32 v148, s[60:61], v226, v226, 1.0
	v_rcp_f32_e32 v149, v148
	s_nop 0
	v_fma_f32 v150, -v148, v149, 1.0
	v_fmac_f32_e32 v149, v150, v149
	v_div_scale_f32 v150, vcc, 1.0, v226, 1.0
	v_mul_f32_e32 v151, v150, v149
	v_fma_f32 v173, -v148, v151, v150
	v_fmac_f32_e32 v151, v173, v149
	v_fma_f32 v148, -v148, v151, v150
	s_nop 1
	v_div_fmas_f32 v148, v148, v149, v151
	v_div_fixup_f32 v166, v148, v226, 1.0
	v_pk_mul_f32 v[0:1], v[0:1], v[166:167] op_sel_hi:[1,0]
	v_pk_mul_f32 v[2:3], v[2:3], v[166:167] op_sel_hi:[1,0]
	v_pk_mul_f32 v[4:5], v[4:5], v[166:167] op_sel_hi:[1,0]
	v_pk_mul_f32 v[6:7], v[6:7], v[166:167] op_sel_hi:[1,0]
	v_pk_mul_f32 v[8:9], v[8:9], v[166:167] op_sel_hi:[1,0]
	v_pk_mul_f32 v[10:11], v[10:11], v[166:167] op_sel_hi:[1,0]
	v_pk_mul_f32 v[12:13], v[12:13], v[166:167] op_sel_hi:[1,0]
	v_pk_mul_f32 v[14:15], v[14:15], v[166:167] op_sel_hi:[1,0]
	v_pk_mul_f32 v[16:17], v[16:17], v[166:167] op_sel_hi:[1,0]
	v_pk_mul_f32 v[18:19], v[18:19], v[166:167] op_sel_hi:[1,0]
	v_pk_mul_f32 v[20:21], v[20:21], v[166:167] op_sel_hi:[1,0]
	v_pk_mul_f32 v[22:23], v[22:23], v[166:167] op_sel_hi:[1,0]
	v_pk_mul_f32 v[24:25], v[24:25], v[166:167] op_sel_hi:[1,0]
	v_pk_mul_f32 v[26:27], v[26:27], v[166:167] op_sel_hi:[1,0]
	v_pk_mul_f32 v[28:29], v[28:29], v[166:167] op_sel_hi:[1,0]
	v_pk_mul_f32 v[30:31], v[30:31], v[166:167] op_sel_hi:[1,0]
	v_cvt_pk_bf16_f32 v96, v0, v1
	v_cvt_pk_bf16_f32 v97, v2, v3
	v_cvt_pk_bf16_f32 v98, v4, v5
	v_cvt_pk_bf16_f32 v99, v6, v7
	v_cvt_pk_bf16_f32 v100, v16, v17
	v_cvt_pk_bf16_f32 v101, v18, v19
	v_cvt_pk_bf16_f32 v102, v20, v21
	v_cvt_pk_bf16_f32 v103, v22, v23
	v_cvt_pk_bf16_f32 v104, v8, v9
	v_cvt_pk_bf16_f32 v105, v10, v11
	v_cvt_pk_bf16_f32 v106, v12, v13
	v_cvt_pk_bf16_f32 v107, v14, v15
	v_cvt_pk_bf16_f32 v108, v24, v25
	v_cvt_pk_bf16_f32 v109, v26, v27
	v_cvt_pk_bf16_f32 v110, v28, v29
	v_cvt_pk_bf16_f32 v111, v30, v31
	s_nop 1
	v_permlane32_swap_b32_e32 v96, v98
	v_permlane32_swap_b32_e32 v97, v99
	v_permlane32_swap_b32_e32 v100, v102
	v_permlane32_swap_b32_e32 v101, v103
	v_permlane32_swap_b32_e32 v104, v106
	v_permlane32_swap_b32_e32 v105, v107
	v_permlane32_swap_b32_e32 v108, v110
	v_permlane32_swap_b32_e32 v109, v111
	global_store_dwordx4 v172, v[96:99], s[16:17]
	global_store_dwordx4 v172, v[100:103], s[16:17] offset:64
	global_store_dwordx4 v172, v[104:107], s[16:17] offset:32
	global_store_dwordx4 v172, v[108:111], s[16:17] offset:96
	s_mov_b32 s6, s59
	s_mov_b64 s[16:17], s[62:63]
	s_cmp_ge_i32 s6, s8
	s_cbranch_scc0 .Lamla_item

; template <bool MLA>
; DI void attn_phase(const int TID, const int BID, LAS unsigned char* lds, const Params& p, bool need_ctx) {
;     ...
;     const int tid = TID, wid = tid >> 6, lane = tid & 63, r = lane & 31, hh = lane >> 5;
;     const int n_items = 1024 + (need_ctx ? 128 : 0);
;     bf16_t* O = P_WSB(OFF_H);
;     for (int item = BID; item < n_items; item += gridDim.x) {
;         int b, head, row0, nk;
;         if (item < 1024) {
;             const int rnd = item >> 8, w = item & 255, xcd = w & 7, slot = w >> 3, qb = slot & 7;
;             if (MLA) { const int grp = (rnd * 8 + xcd) * 4 + (slot >> 3); b = grp >> 4; head = grp & 15; }
;             else { const int grp = rnd * 8 + xcd; b = grp >> 2; head = (grp & 3) * 4 + (slot >> 3); }
;             row0 = b * 2048 + qb * 256; nk = NKEY;
;         }
;         else { const int it = item - 1024; b = it >> 4; head = it & 15; row0 = TL + b * 256; nk = 256; }
;         const int kvh = MLA ? head : (head >> 2);
;         const bf16_t* Kb = P_WSB(OFF_K) + (size_t)(b * NKV + kvh) * NKEY * 64;
;         const bf16_t* Vb = P_WSB(OFF_VT) + (size_t)(b * NKV + kvh) * NKEY * 64;
;         const bf16_t* Pb = P_WSB(OFF_KPE) + (size_t)b * NKEY * 32;
;         bf16x8 qf[NKS];
;         {
;             const bf16_t* qp = P_WSB(OFF_Q) + (size_t)(row0 + wid * 32 + r) * QS + head * DK + hh * 8;
; #pragma unroll
;             for (int ks = 0; ks < NKS; ++ks) qf[ks] = *(const bf16x8*)(qp + ks * 16);
;         }
;         u32x4 kreg, vreg; u32x2 preg = {0u, 0u};
.LBB0_318:
	s_andn2_b64 vcc, exec, s[4:5]
	s_cbranch_vccnz .LBB0_339
	s_and_b64 vcc, exec, s[2:3]
	s_cbranch_vccnz .LBB0_339
	v_and_b32_e32 v208, 31, v174
	v_bfe_u32 v209, v174, 5, 1
	v_lshrrev_b32_e32 v210, 6, v174
	v_lshrrev_b32_e32 v211, 3, v174
	v_and_b32_e32 v212, 7, v174
	v_mov_b32_e32 v213, s23
	s_movk_i32 s15, 0x90
	v_mad_u32_u24 v243, v208, s15, v213
	v_lshl_add_u32 v243, v209, 4, v243
	v_mad_u32_u24 v218, v211, s15, v213
	v_lshl_add_u32 v218, v212, 4, v218
	s_movk_i32 s15, 0xc0
	v_bfe_u32 v214, v174, 2, 2
	v_lshl_add_u32 v214, v209, 2, v214
	v_mad_u32_u24 v220, v214, s15, v213
	v_bfe_u32 v215, v174, 4, 1
	v_and_b32_e32 v216, 3, v174
	v_lshlrev_b32_e32 v215, 5, v215
	v_lshl_add_u32 v215, v216, 3, v215
	v_add_u32_e32 v220, v220, v215
	v_add_u32_e32 v220, 0x4800, v220
	v_mad_u32_u24 v221, v211, s15, v213
	v_lshl_add_u32 v221, v212, 4, v221
	v_add_u32_e32 v221, 0x4800, v221
	v_lshlrev_b32_e32 v225, 7, v211
	v_lshl_add_u32 v225, v212, 4, v225
	v_lshl_add_u32 v217, v210, 5, v208
	s_movk_i32 s15, 0x800
	v_mul_u32_u24_e32 v171, s15, v217
	v_lshl_add_u32 v171, v209, 4, v171
	v_lshlrev_b32_e32 v172, 11, v217
	v_lshl_add_u32 v172, v209, 4, v172
	v_mov_b32_e32 v167, 0
	v_and_b32_e32 v214, 15, v174
	v_bfe_u32 v215, v174, 4, 1
	v_cmp_eq_u32_e32 vcc, v214, v215
	v_mov_b32_e32 v216, 0x3f803f80
	s_nop 1
	v_cndmask_b32_e32 v246, 0, v216, vcc
	v_cndmask_b32_e32 v247, 0, v216, vcc
	v_cndmask_b32_e32 v248, 0, v216, vcc
	v_cndmask_b32_e32 v249, 0, v216, vcc
	v_lshlrev_b32_e32 v230, 2, v214
	v_add_u32_e32 v231, 64, v230
	v_readfirstlane_b32 s58, v210
	s_mov_b32 s6, s83
	s_lshr_b32 s58, s58, 2
	s_cmpk_gt_i32 s6, 0x3ff
	s_cbranch_scc0 .Lagqa_mainitem_first
	s_add_i32 s21, s6, 0xfffffc00
	s_lshr_b32 s15, s21, 4
	s_and_b32 s18, s21, 15
	s_lshl_b32 s20, s15, 8
	s_add_i32 s20, s20, 0x4000
	s_mov_b32 s7, 0
	s_branch .Lagqa_decoded_first

; #define AT_GLOADK(k0) do { kreg = *(const u32x4*)(Kb + (size_t)((k0) + (tid >> 3)) * 64 + (tid & 7) * 8); \
;             if (MLA) preg = *(const u32x2*)(Pb + (size_t)((k0) + (tid >> 3)) * 32 + (tid & 7) * 4); } while (0)
; #define AT_GLOADV(k0) do { vreg = *(const u32x4*)(Vb + (size_t)((k0) + (tid >> 3)) * 64 + (tid & 7) * 8); } while (0)
; #define AT_WRITEK(buf) do { *(LAS u32x4*)(lds + (buf) * KBUF + (tid >> 3) * KSTR + (tid & 7) * 16) = kreg; \
;             if (MLA) *(LAS u32x2*)(lds + (buf) * KBUF + (tid >> 3) * KSTR + 128 + (tid & 7) * 8) = preg; } while (0)
; #define AT_WRITEV(buf) do { *(LAS u32x4*)(lds + 2 * KBUF + (buf) * VBUF + (tid >> 3) * VSTR + (tid & 7) * 16) = vreg; } while (0)
; template <bool MLA>
; DI void attn_phase(const int TID, const int BID, LAS unsigned char* lds, const Params& p, bool need_ctx) {
;     ...
;         f32x16 o0, o1, sa0, sa1, sb0, sb1;
; #pragma unroll
;         for (int j = 0; j < 16; ++j) { o0[j] = 0.f; o1[j] = 0.f; }
;         float mrun = -1e30f, lsum = 0.f;
;         if (wid >= 4) __builtin_amdgcn_s_setprio(1);
;         const int ntile = nk >> 6;
;         AT_GLOADK(0); AT_GLOADV(0); AT_WRITEK(0); AT_WRITEV(0);
;         AT_GLOADK(64); AT_WRITEK(1);
;         __syncthreads();
;         AT_QK(sa0, sa1, 0);
;         __syncthreads();
.Lagqa_item:
	s_mov_b32 s52, 0x3000
	s_mov_b32 s53, 0x6000
	s_mov_b32 s54, 0
	v_mov_b64_e32 v[0:1], 0
	v_mov_b64_e32 v[2:3], 0
	v_mov_b64_e32 v[4:5], 0
	v_mov_b64_e32 v[6:7], 0
	v_mov_b64_e32 v[8:9], 0
	v_mov_b64_e32 v[10:11], 0
	v_mov_b64_e32 v[12:13], 0
	v_mov_b64_e32 v[14:15], 0
	v_mov_b64_e32 v[16:17], 0
	v_mov_b64_e32 v[18:19], 0
	v_mov_b64_e32 v[20:21], 0
	v_mov_b64_e32 v[22:23], 0
	v_mov_b64_e32 v[24:25], 0
	v_mov_b64_e32 v[26:27], 0
	v_mov_b64_e32 v[28:29], 0
	v_mov_b64_e32 v[30:31], 0
	v_mov_b32_e32 v162, 0xf149f2ca
	v_mov_b32_e32 v164, 0xf149f2ca
	v_mov_b32_e32 v163, 0x7149f2ca
	v_mov_b64_e32 v[226:227], 0
	v_mov_b64_e32 v[228:229], 0
	s_barrier
	s_waitcnt vmcnt(4)
	ds_write_b128 v218, v[136:139]
	s_waitcnt vmcnt(3)
	ds_write_b128 v218, v[140:143] offset:9216
	s_waitcnt vmcnt(2)
	ds_write_b128 v221, v[144:147]
	s_waitcnt lgkmcnt(0)
	s_barrier
	s_cmp_eq_u32 s58, 0
	s_cbranch_scc1 .Lagqa_prio
	s_setprio 1

.Lagqa_loop:
	ds_read_b128 v[136:139], v243 offset:0
	ds_read_b128 v[140:143], v243 offset:4608
	ds_read_b128 v[144:147], v243 offset:32
	ds_read_b128 v[148:151], v243 offset:4640
	s_waitcnt lgkmcnt(10)
	v_mfma_f32_32x32x16_bf16 v[0:15], v[176:179], v[96:99], v[0:15]
	v_max3_f32 v168, v64, v65, v66
	v_max3_f32 v170, v80, v81, v82
	v_max3_f32 v168, v168, v67, v68
	v_max3_f32 v170, v170, v83, v84
	v_max3_f32 v168, v168, v69, v70
	v_max3_f32 v170, v170, v85, v86
	v_max3_f32 v168, v168, v71, v72
	s_mov_b32 s55, s52
	s_mov_b32 s52, s53
	s_mov_b32 s53, s54
	s_mov_b32 s54, s55
	s_mov_b32 s9, 0
	s_waitcnt lgkmcnt(8)
	v_mfma_f32_32x32x16_bf16 v[16:31], v[180:183], v[96:99], v[16:31]
	v_max3_f32 v170, v170, v87, v88
	v_max3_f32 v168, v168, v73, v74
	v_max3_f32 v170, v170, v89, v90
	v_max3_f32 v168, v168, v75, v76
	v_max3_f32 v170, v170, v91, v92
	v_max3_f32 v168, v168, v77, v78
	v_max3_f32 v170, v170, v93, v94
	global_load_dwordx4 v[152:155], v225, s[2:3]
	global_load_dwordx4 v[156:159], v225, s[4:5]
	s_add_u32 s2, s2, 0x2000
	s_addc_u32 s3, s3, 0
	s_add_u32 s4, s4, 0x2000
	s_addc_u32 s5, s5, 0
	v_add_u32_e32 v222, s53, v220
	v_add_u32_e32 v224, s54, v221
	v_mfma_f32_16x16x32_bf16 v[226:229], v[246:249], v[96:99], v[226:229]
	v_max_f32_e32 v168, v168, v79
	v_max_f32_e32 v170, v170, v95
	v_max_f32_e32 v168, v168, v170
	v_mov_b32_e32 v170, v168
	s_nop 1
	v_permlane32_swap_b32_e32 v168, v170
	v_max_f32_e32 v168, v168, v170
	v_mul_f32_e32 v168, 0x3e38aa3b, v168
	s_waitcnt lgkmcnt(3)
	v_mfma_f32_32x32x16_bf16 v[32:47], v[136:139], v[112:115], 0
	v_cmp_gt_f32_e32 vcc, v168, v164
	s_cbranch_vccz .Lagqa_nors_2
	v_max_f32_e32 v170, v162, v168
	v_sub_f32_e32 v166, v162, v170
	v_exp_f32_e32 v166, v166
	v_mov_b32_e32 v162, v170
	v_add_f32_e32 v164, 0x41000000, v170
	v_xor_b32_e32 v163, 0x80000000, v170
	s_mov_b32 s9, 1
.Lagqa_nors_2:
	v_fmamk_f32 v64, v64, 0x3e38aa3b, v163
	v_fmamk_f32 v80, v80, 0x3e38aa3b, v163
	v_exp_f32_e32 v64, v64
	ds_read_b128 v[136:139], v243 offset:64
	ds_read_b64_tr_b16 v[192:193], v223 offset:3072
	ds_read_b64_tr_b16 v[194:195], v223 offset:4608
	v_mfma_f32_32x32x16_bf16 v[0:15], v[184:187], v[104:107], v[0:15]
	v_exp_f32_e32 v80, v80
	v_fmamk_f32 v65, v65, 0x3e38aa3b, v163
	v_fmamk_f32 v81, v81, 0x3e38aa3b, v163
	v_exp_f32_e32 v65, v65
	v_exp_f32_e32 v81, v81
	ds_read_b64_tr_b16 v[196:197], v223 offset:3136
	ds_read_b64_tr_b16 v[198:199], v223 offset:4672
	s_waitcnt lgkmcnt(7)
	v_mfma_f32_32x32x16_bf16 v[48:63], v[140:143], v[112:115], 0
	v_fmamk_f32 v66, v66, 0x3e38aa3b, v163
	v_fmamk_f32 v82, v82, 0x3e38aa3b, v163
	v_exp_f32_e32 v66, v66
	v_exp_f32_e32 v82, v82
	ds_read_b128 v[140:143], v243 offset:4672
	ds_read_b64_tr_b16 v[200:201], v223 offset:9216
	ds_read_b64_tr_b16 v[202:203], v223 offset:10752
	v_mfma_f32_32x32x16_bf16 v[16:31], v[188:191], v[104:107], v[16:31]
	v_cvt_pk_bf16_f32 v96, v64, v65
	v_fmamk_f32 v67, v67, 0x3e38aa3b, v163
	v_fmamk_f32 v83, v83, 0x3e38aa3b, v163
	v_exp_f32_e32 v67, v67
	v_exp_f32_e32 v83, v83
	ds_read_b64_tr_b16 v[204:205], v223 offset:9280
	ds_read_b64_tr_b16 v[206:207], v223 offset:10816
	s_waitcnt lgkmcnt(11)
	v_mfma_f32_32x32x16_bf16 v[32:47], v[144:147], v[116:119], v[32:47]
	v_fmamk_f32 v68, v68, 0x3e38aa3b, v163
	v_fmamk_f32 v84, v84, 0x3e38aa3b, v163
	v_exp_f32_e32 v68, v68
	v_exp_f32_e32 v84, v84
	ds_read_b128 v[144:147], v243 offset:96
	v_mfma_f32_16x16x32_bf16 v[226:229], v[246:249], v[104:107], v[226:229]
	v_cvt_pk_bf16_f32 v104, v80, v81
	v_cvt_pk_bf16_f32 v97, v66, v67
	v_cvt_pk_bf16_f32 v105, v82, v83
	v_fmamk_f32 v69, v69, 0x3e38aa3b, v163
	v_fmamk_f32 v85, v85, 0x3e38aa3b, v163
	v_exp_f32_e32 v69, v69
	v_exp_f32_e32 v85, v85
	s_waitcnt lgkmcnt(11)
	v_mfma_f32_32x32x16_bf16 v[48:63], v[148:151], v[116:119], v[48:63]
	v_fmamk_f32 v70, v70, 0x3e38aa3b, v163
	v_fmamk_f32 v86, v86, 0x3e38aa3b, v163
	v_exp_f32_e32 v70, v70
	v_exp_f32_e32 v86, v86
	ds_read_b128 v[148:151], v243 offset:4704
	s_waitcnt lgkmcnt(9)
	v_mfma_f32_32x32x16_bf16 v[0:15], v[192:195], v[100:103], v[0:15]
	v_cvt_pk_bf16_f32 v98, v68, v69
	v_cvt_pk_bf16_f32 v106, v84, v85
	v_fmamk_f32 v71, v71, 0x3e38aa3b, v163
	v_fmamk_f32 v87, v87, 0x3e38aa3b, v163
	v_exp_f32_e32 v71, v71
	v_exp_f32_e32 v87, v87
	v_mfma_f32_32x32x16_bf16 v[32:47], v[136:139], v[120:123], v[32:47]
	v_fmamk_f32 v72, v72, 0x3e38aa3b, v163
	v_fmamk_f32 v88, v88, 0x3e38aa3b, v163
	v_exp_f32_e32 v72, v72
	v_exp_f32_e32 v88, v88
	s_waitcnt vmcnt(3)
	ds_write_b128 v218, v[208:211] offset:9216
	s_waitcnt vmcnt(2)
	ds_write_b128 v224, v[212:215]
	s_waitcnt lgkmcnt(9)
	v_mfma_f32_32x32x16_bf16 v[16:31], v[196:199], v[100:103], v[16:31]
	v_cvt_pk_bf16_f32 v99, v70, v71
	v_cvt_pk_bf16_f32 v107, v86, v87
	v_fmamk_f32 v73, v73, 0x3e38aa3b, v163
	v_fmamk_f32 v89, v89, 0x3e38aa3b, v163
	v_exp_f32_e32 v73, v73
	s_waitcnt lgkmcnt(8)
	v_mfma_f32_32x32x16_bf16 v[48:63], v[140:143], v[120:123], v[48:63]
	v_exp_f32_e32 v89, v89
	v_fmamk_f32 v74, v74, 0x3e38aa3b, v163
	v_fmamk_f32 v90, v90, 0x3e38aa3b, v163
	v_exp_f32_e32 v74, v74
	v_exp_f32_e32 v90, v90
	v_mfma_f32_16x16x32_bf16 v[226:229], v[246:249], v[100:103], v[226:229]
	v_cvt_pk_bf16_f32 v100, v72, v73
	v_fmamk_f32 v75, v75, 0x3e38aa3b, v163
	v_fmamk_f32 v91, v91, 0x3e38aa3b, v163
	v_exp_f32_e32 v75, v75
	v_exp_f32_e32 v91, v91
	ds_read_b64_tr_b16 v[176:177], v222 offset:0
	ds_read_b64_tr_b16 v[178:179], v222 offset:1536
	s_waitcnt lgkmcnt(5)
	v_mfma_f32_32x32x16_bf16 v[32:47], v[144:147], v[124:127], v[32:47]
	v_fmamk_f32 v76, v76, 0x3e38aa3b, v163
	v_fmamk_f32 v92, v92, 0x3e38aa3b, v163
	v_exp_f32_e32 v76, v76
	v_exp_f32_e32 v92, v92
	ds_read_b64_tr_b16 v[180:181], v222 offset:64
	ds_read_b64_tr_b16 v[182:183], v222 offset:1600
	v_mfma_f32_32x32x16_bf16 v[0:15], v[200:203], v[108:111], v[0:15]
	v_cvt_pk_bf16_f32 v101, v74, v75
	v_fmamk_f32 v77, v77, 0x3e38aa3b, v163
	v_fmamk_f32 v93, v93, 0x3e38aa3b, v163
	v_exp_f32_e32 v77, v77
	v_exp_f32_e32 v93, v93
	ds_read_b64_tr_b16 v[184:185], v222 offset:6144
	ds_read_b64_tr_b16 v[186:187], v222 offset:7680
	s_waitcnt lgkmcnt(8)
	v_mfma_f32_32x32x16_bf16 v[48:63], v[148:151], v[124:127], v[48:63]
	v_fmamk_f32 v78, v78, 0x3e38aa3b, v163
	v_fmamk_f32 v94, v94, 0x3e38aa3b, v163
	v_exp_f32_e32 v78, v78
	v_exp_f32_e32 v94, v94
	ds_read_b64_tr_b16 v[188:189], v222 offset:6208
	ds_read_b64_tr_b16 v[190:191], v222 offset:7744
	v_mfma_f32_32x32x16_bf16 v[16:31], v[204:207], v[108:111], v[16:31]
	v_cvt_pk_bf16_f32 v102, v76, v77
	v_fmamk_f32 v79, v79, 0x3e38aa3b, v163
	v_fmamk_f32 v95, v95, 0x3e38aa3b, v163
	v_exp_f32_e32 v79, v79
	v_exp_f32_e32 v95, v95
	v_mfma_f32_16x16x32_bf16 v[226:229], v[246:249], v[108:111], v[226:229]
	v_cvt_pk_bf16_f32 v108, v88, v89
	v_cvt_pk_bf16_f32 v109, v90, v91
	v_cvt_pk_bf16_f32 v110, v92, v93
	v_cvt_pk_bf16_f32 v103, v78, v79
	v_cvt_pk_bf16_f32 v111, v94, v95
	s_cmp_lg_u32 s9, 0
	s_cbranch_scc0 .Lagqa_noresc_3
	s_nop 15
	v_pk_mul_f32 v[0:1], v[0:1], v[166:167] op_sel_hi:[1,0]
	v_pk_mul_f32 v[2:3], v[2:3], v[166:167] op_sel_hi:[1,0]
	v_pk_mul_f32 v[4:5], v[4:5], v[166:167] op_sel_hi:[1,0]
	v_pk_mul_f32 v[6:7], v[6:7], v[166:167] op_sel_hi:[1,0]
	v_pk_mul_f32 v[8:9], v[8:9], v[166:167] op_sel_hi:[1,0]
	v_pk_mul_f32 v[10:11], v[10:11], v[166:167] op_sel_hi:[1,0]
	v_pk_mul_f32 v[12:13], v[12:13], v[166:167] op_sel_hi:[1,0]
	v_pk_mul_f32 v[14:15], v[14:15], v[166:167] op_sel_hi:[1,0]
	v_pk_mul_f32 v[16:17], v[16:17], v[166:167] op_sel_hi:[1,0]
	v_pk_mul_f32 v[18:19], v[18:19], v[166:167] op_sel_hi:[1,0]
	v_pk_mul_f32 v[20:21], v[20:21], v[166:167] op_sel_hi:[1,0]
	v_pk_mul_f32 v[22:23], v[22:23], v[166:167] op_sel_hi:[1,0]
	v_pk_mul_f32 v[24:25], v[24:25], v[166:167] op_sel_hi:[1,0]
	v_pk_mul_f32 v[26:27], v[26:27], v[166:167] op_sel_hi:[1,0]
	v_pk_mul_f32 v[28:29], v[28:29], v[166:167] op_sel_hi:[1,0]
	v_pk_mul_f32 v[30:31], v[30:31], v[166:167] op_sel_hi:[1,0]
	ds_bpermute_b32 v173, v231, v166
	v_mul_f32_e32 v226, v226, v166
	s_waitcnt lgkmcnt(0)
	v_mul_f32_e32 v227, v227, v173
.Lagqa_noresc_3:
	s_waitcnt lgkmcnt(8)
	s_barrier
	ds_read_b128 v[136:139], v243 offset:9216
	ds_read_b128 v[140:143], v243 offset:13824
	ds_read_b128 v[144:147], v243 offset:9248
	ds_read_b128 v[148:151], v243 offset:13856
	s_waitcnt lgkmcnt(10)
	v_mfma_f32_32x32x16_bf16 v[0:15], v[176:179], v[96:99], v[0:15]
	v_max3_f32 v168, v32, v33, v34
	v_max3_f32 v170, v48, v49, v50
	v_max3_f32 v168, v168, v35, v36
	v_max3_f32 v170, v170, v51, v52
	v_max3_f32 v168, v168, v37, v38
	v_max3_f32 v170, v170, v53, v54
	v_max3_f32 v168, v168, v39, v40
	s_mov_b32 s55, s52
	s_mov_b32 s52, s53
	s_mov_b32 s53, s54
	s_mov_b32 s54, s55
	s_mov_b32 s9, 0
	s_waitcnt lgkmcnt(8)
	v_mfma_f32_32x32x16_bf16 v[16:31], v[180:183], v[96:99], v[16:31]
	v_max3_f32 v170, v170, v55, v56
	v_max3_f32 v168, v168, v41, v42
	v_max3_f32 v170, v170, v57, v58
	v_max3_f32 v168, v168, v43, v44
	v_max3_f32 v170, v170, v59, v60
	v_max3_f32 v168, v168, v45, v46
	v_max3_f32 v170, v170, v61, v62
	global_load_dwordx4 v[208:211], v225, s[2:3]
	global_load_dwordx4 v[212:215], v225, s[4:5]
	s_add_u32 s2, s2, 0x2000
	s_addc_u32 s3, s3, 0
	s_add_u32 s4, s4, 0x2000
	s_addc_u32 s5, s5, 0
	v_add_u32_e32 v223, s53, v220
	v_add_u32_e32 v224, s54, v221
	v_mfma_f32_16x16x32_bf16 v[226:229], v[246:249], v[96:99], v[226:229]
	v_max_f32_e32 v168, v168, v47
	v_max_f32_e32 v170, v170, v63
	v_max_f32_e32 v168, v168, v170
	v_mov_b32_e32 v170, v168
	s_nop 1
	v_permlane32_swap_b32_e32 v168, v170
	v_max_f32_e32 v168, v168, v170
	v_mul_f32_e32 v168, 0x3e38aa3b, v168
	s_waitcnt lgkmcnt(3)
	v_mfma_f32_32x32x16_bf16 v[64:79], v[136:139], v[112:115], 0
	v_cmp_gt_f32_e32 vcc, v168, v164
	s_cbranch_vccz .Lagqa_nors_4
	v_max_f32_e32 v170, v162, v168
	v_sub_f32_e32 v166, v162, v170
	v_exp_f32_e32 v166, v166
	v_mov_b32_e32 v162, v170
	v_add_f32_e32 v164, 0x41000000, v170
	v_xor_b32_e32 v163, 0x80000000, v170
	s_mov_b32 s9, 1
.Lagqa_nors_4:
	v_fmamk_f32 v32, v32, 0x3e38aa3b, v163
	v_fmamk_f32 v48, v48, 0x3e38aa3b, v163
	v_exp_f32_e32 v32, v32
	ds_read_b128 v[136:139], v243 offset:9280
	ds_read_b64_tr_b16 v[192:193], v222 offset:3072
	ds_read_b64_tr_b16 v[194:195], v222 offset:4608
	v_mfma_f32_32x32x16_bf16 v[0:15], v[184:187], v[104:107], v[0:15]
	v_exp_f32_e32 v48, v48
	v_fmamk_f32 v33, v33, 0x3e38aa3b, v163
	v_fmamk_f32 v49, v49, 0x3e38aa3b, v163
	v_exp_f32_e32 v33, v33
	v_exp_f32_e32 v49, v49
	ds_read_b64_tr_b16 v[196:197], v222 offset:3136
	ds_read_b64_tr_b16 v[198:199], v222 offset:4672
	s_waitcnt lgkmcnt(7)
	v_mfma_f32_32x32x16_bf16 v[80:95], v[140:143], v[112:115], 0
	v_fmamk_f32 v34, v34, 0x3e38aa3b, v163
	v_fmamk_f32 v50, v50, 0x3e38aa3b, v163
	v_exp_f32_e32 v34, v34
	v_exp_f32_e32 v50, v50
	ds_read_b128 v[140:143], v243 offset:13888
	ds_read_b64_tr_b16 v[200:201], v222 offset:9216
	ds_read_b64_tr_b16 v[202:203], v222 offset:10752
	v_mfma_f32_32x32x16_bf16 v[16:31], v[188:191], v[104:107], v[16:31]
	v_cvt_pk_bf16_f32 v96, v32, v33
	v_fmamk_f32 v35, v35, 0x3e38aa3b, v163
	v_fmamk_f32 v51, v51, 0x3e38aa3b, v163
	v_exp_f32_e32 v35, v35
	v_exp_f32_e32 v51, v51
	ds_read_b64_tr_b16 v[204:205], v222 offset:9280
	ds_read_b64_tr_b16 v[206:207], v222 offset:10816
	s_waitcnt lgkmcnt(11)
	v_mfma_f32_32x32x16_bf16 v[64:79], v[144:147], v[116:119], v[64:79]
	v_fmamk_f32 v36, v36, 0x3e38aa3b, v163
	v_fmamk_f32 v52, v52, 0x3e38aa3b, v163
	v_exp_f32_e32 v36, v36
	v_exp_f32_e32 v52, v52
	ds_read_b128 v[144:147], v243 offset:9312
	v_mfma_f32_16x16x32_bf16 v[226:229], v[246:249], v[104:107], v[226:229]
	v_cvt_pk_bf16_f32 v104, v48, v49
	v_cvt_pk_bf16_f32 v97, v34, v35
	v_cvt_pk_bf16_f32 v105, v50, v51
	v_fmamk_f32 v37, v37, 0x3e38aa3b, v163
	v_fmamk_f32 v53, v53, 0x3e38aa3b, v163
	v_exp_f32_e32 v37, v37
	v_exp_f32_e32 v53, v53
	s_waitcnt lgkmcnt(11)
	v_mfma_f32_32x32x16_bf16 v[80:95], v[148:151], v[116:119], v[80:95]
	v_fmamk_f32 v38, v38, 0x3e38aa3b, v163
	v_fmamk_f32 v54, v54, 0x3e38aa3b, v163
	v_exp_f32_e32 v38, v38
	v_exp_f32_e32 v54, v54
	ds_read_b128 v[148:151], v243 offset:13920
	s_waitcnt lgkmcnt(9)
	v_mfma_f32_32x32x16_bf16 v[0:15], v[192:195], v[100:103], v[0:15]
	v_cvt_pk_bf16_f32 v98, v36, v37
	v_cvt_pk_bf16_f32 v106, v52, v53
	v_fmamk_f32 v39, v39, 0x3e38aa3b, v163
	v_fmamk_f32 v55, v55, 0x3e38aa3b, v163
	v_exp_f32_e32 v39, v39
	v_exp_f32_e32 v55, v55
	v_mfma_f32_32x32x16_bf16 v[64:79], v[136:139], v[120:123], v[64:79]
	v_fmamk_f32 v40, v40, 0x3e38aa3b, v163
	v_fmamk_f32 v56, v56, 0x3e38aa3b, v163
	v_exp_f32_e32 v40, v40
	v_exp_f32_e32 v56, v56
	s_waitcnt vmcnt(3)
	ds_write_b128 v218, v[152:155]
	s_waitcnt vmcnt(2)
	ds_write_b128 v224, v[156:159]
	s_waitcnt lgkmcnt(9)
	v_mfma_f32_32x32x16_bf16 v[16:31], v[196:199], v[100:103], v[16:31]
	v_cvt_pk_bf16_f32 v99, v38, v39
	v_cvt_pk_bf16_f32 v107, v54, v55
	v_fmamk_f32 v41, v41, 0x3e38aa3b, v163
	v_fmamk_f32 v57, v57, 0x3e38aa3b, v163
	v_exp_f32_e32 v41, v41
	s_waitcnt lgkmcnt(8)
	v_mfma_f32_32x32x16_bf16 v[80:95], v[140:143], v[120:123], v[80:95]
	v_exp_f32_e32 v57, v57
	v_fmamk_f32 v42, v42, 0x3e38aa3b, v163
	v_fmamk_f32 v58, v58, 0x3e38aa3b, v163
	v_exp_f32_e32 v42, v42
	v_exp_f32_e32 v58, v58
	v_mfma_f32_16x16x32_bf16 v[226:229], v[246:249], v[100:103], v[226:229]
	v_cvt_pk_bf16_f32 v100, v40, v41
	v_fmamk_f32 v43, v43, 0x3e38aa3b, v163
	v_fmamk_f32 v59, v59, 0x3e38aa3b, v163
	v_exp_f32_e32 v43, v43
	v_exp_f32_e32 v59, v59
	ds_read_b64_tr_b16 v[176:177], v223 offset:0
	ds_read_b64_tr_b16 v[178:179], v223 offset:1536
	s_waitcnt lgkmcnt(5)
	v_mfma_f32_32x32x16_bf16 v[64:79], v[144:147], v[124:127], v[64:79]
	v_fmamk_f32 v44, v44, 0x3e38aa3b, v163
	v_fmamk_f32 v60, v60, 0x3e38aa3b, v163
	v_exp_f32_e32 v44, v44
	v_exp_f32_e32 v60, v60
	ds_read_b64_tr_b16 v[180:181], v223 offset:64
	ds_read_b64_tr_b16 v[182:183], v223 offset:1600
	v_mfma_f32_32x32x16_bf16 v[0:15], v[200:203], v[108:111], v[0:15]
	v_cvt_pk_bf16_f32 v101, v42, v43
	v_fmamk_f32 v45, v45, 0x3e38aa3b, v163
	v_fmamk_f32 v61, v61, 0x3e38aa3b, v163
	v_exp_f32_e32 v45, v45
	v_exp_f32_e32 v61, v61
	ds_read_b64_tr_b16 v[184:185], v223 offset:6144
	ds_read_b64_tr_b16 v[186:187], v223 offset:7680
	s_waitcnt lgkmcnt(8)
	v_mfma_f32_32x32x16_bf16 v[80:95], v[148:151], v[124:127], v[80:95]
	v_fmamk_f32 v46, v46, 0x3e38aa3b, v163
	v_fmamk_f32 v62, v62, 0x3e38aa3b, v163
	v_exp_f32_e32 v46, v46
	v_exp_f32_e32 v62, v62
	ds_read_b64_tr_b16 v[188:189], v223 offset:6208
	ds_read_b64_tr_b16 v[190:191], v223 offset:7744
	v_mfma_f32_32x32x16_bf16 v[16:31], v[204:207], v[108:111], v[16:31]
	v_cvt_pk_bf16_f32 v102, v44, v45
	v_fmamk_f32 v47, v47, 0x3e38aa3b, v163
	v_fmamk_f32 v63, v63, 0x3e38aa3b, v163
	v_exp_f32_e32 v47, v47
	v_exp_f32_e32 v63, v63
	v_mfma_f32_16x16x32_bf16 v[226:229], v[246:249], v[108:111], v[226:229]
	v_cvt_pk_bf16_f32 v108, v56, v57
	v_cvt_pk_bf16_f32 v109, v58, v59
	v_cvt_pk_bf16_f32 v110, v60, v61
	v_cvt_pk_bf16_f32 v103, v46, v47
	v_cvt_pk_bf16_f32 v111, v62, v63
	s_cmp_lg_u32 s9, 0
	s_cbranch_scc0 .Lagqa_noresc_5
	s_nop 15
	v_pk_mul_f32 v[0:1], v[0:1], v[166:167] op_sel_hi:[1,0]
	v_pk_mul_f32 v[2:3], v[2:3], v[166:167] op_sel_hi:[1,0]
	v_pk_mul_f32 v[4:5], v[4:5], v[166:167] op_sel_hi:[1,0]
	v_pk_mul_f32 v[6:7], v[6:7], v[166:167] op_sel_hi:[1,0]
	v_pk_mul_f32 v[8:9], v[8:9], v[166:167] op_sel_hi:[1,0]
	v_pk_mul_f32 v[10:11], v[10:11], v[166:167] op_sel_hi:[1,0]
	v_pk_mul_f32 v[12:13], v[12:13], v[166:167] op_sel_hi:[1,0]
	v_pk_mul_f32 v[14:15], v[14:15], v[166:167] op_sel_hi:[1,0]
	v_pk_mul_f32 v[16:17], v[16:17], v[166:167] op_sel_hi:[1,0]
	v_pk_mul_f32 v[18:19], v[18:19], v[166:167] op_sel_hi:[1,0]
	v_pk_mul_f32 v[20:21], v[20:21], v[166:167] op_sel_hi:[1,0]
	v_pk_mul_f32 v[22:23], v[22:23], v[166:167] op_sel_hi:[1,0]
	v_pk_mul_f32 v[24:25], v[24:25], v[166:167] op_sel_hi:[1,0]
	v_pk_mul_f32 v[26:27], v[26:27], v[166:167] op_sel_hi:[1,0]
	v_pk_mul_f32 v[28:29], v[28:29], v[166:167] op_sel_hi:[1,0]
	v_pk_mul_f32 v[30:31], v[30:31], v[166:167] op_sel_hi:[1,0]
	ds_bpermute_b32 v173, v231, v166
	v_mul_f32_e32 v226, v226, v166
	s_waitcnt lgkmcnt(0)
	v_mul_f32_e32 v227, v227, v173

.Lagqa_tail:
	ds_read_b128 v[136:139], v243 offset:0
	ds_read_b128 v[140:143], v243 offset:4608
	ds_read_b128 v[144:147], v243 offset:32
	ds_read_b128 v[148:151], v243 offset:4640
	s_waitcnt lgkmcnt(10)
	v_mfma_f32_32x32x16_bf16 v[0:15], v[176:179], v[96:99], v[0:15]
	v_max3_f32 v168, v64, v65, v66
	v_max3_f32 v170, v80, v81, v82
	v_max3_f32 v168, v168, v67, v68
	v_max3_f32 v170, v170, v83, v84
	v_max3_f32 v168, v168, v69, v70
	v_max3_f32 v170, v170, v85, v86
	v_max3_f32 v168, v168, v71, v72
	s_mov_b32 s55, s52
	s_mov_b32 s52, s53
	s_mov_b32 s53, s54
	s_mov_b32 s54, s55
	s_mov_b32 s9, 0
	s_waitcnt lgkmcnt(8)
	v_mfma_f32_32x32x16_bf16 v[16:31], v[180:183], v[96:99], v[16:31]
	v_max3_f32 v170, v170, v87, v88
	v_max3_f32 v168, v168, v73, v74
	v_max3_f32 v170, v170, v89, v90
	v_max3_f32 v168, v168, v75, v76
	v_max3_f32 v170, v170, v91, v92
	v_max3_f32 v168, v168, v77, v78
	v_max3_f32 v170, v170, v93, v94
	global_load_dwordx4 v[156:159], v225, s[4:5]
	s_add_u32 s4, s4, 0x2000
	s_addc_u32 s5, s5, 0
	v_add_u32_e32 v222, s53, v220
	v_add_u32_e32 v224, s54, v221
	v_mfma_f32_16x16x32_bf16 v[226:229], v[246:249], v[96:99], v[226:229]
	v_max_f32_e32 v168, v168, v79
	v_max_f32_e32 v170, v170, v95
	v_max_f32_e32 v168, v168, v170
	v_mov_b32_e32 v170, v168
	s_nop 1
	v_permlane32_swap_b32_e32 v168, v170
	v_max_f32_e32 v168, v168, v170
	v_mul_f32_e32 v168, 0x3e38aa3b, v168
	s_waitcnt lgkmcnt(3)
	v_mfma_f32_32x32x16_bf16 v[32:47], v[136:139], v[112:115], 0
	v_cmp_gt_f32_e32 vcc, v168, v164
	s_cbranch_vccz .Lagqa_nors_6
	v_max_f32_e32 v170, v162, v168
	v_sub_f32_e32 v166, v162, v170
	v_exp_f32_e32 v166, v166
	v_mov_b32_e32 v162, v170
	v_add_f32_e32 v164, 0x41000000, v170
	v_xor_b32_e32 v163, 0x80000000, v170
	s_mov_b32 s9, 1
.Lagqa_nors_6:
	v_fmamk_f32 v64, v64, 0x3e38aa3b, v163
	v_fmamk_f32 v80, v80, 0x3e38aa3b, v163
	v_exp_f32_e32 v64, v64
	ds_read_b128 v[136:139], v243 offset:64
	ds_read_b64_tr_b16 v[192:193], v223 offset:3072
	ds_read_b64_tr_b16 v[194:195], v223 offset:4608
	v_mfma_f32_32x32x16_bf16 v[0:15], v[184:187], v[104:107], v[0:15]
	v_exp_f32_e32 v80, v80
	v_fmamk_f32 v65, v65, 0x3e38aa3b, v163
	v_fmamk_f32 v81, v81, 0x3e38aa3b, v163
	v_exp_f32_e32 v65, v65
	v_exp_f32_e32 v81, v81
	ds_read_b64_tr_b16 v[196:197], v223 offset:3136
	ds_read_b64_tr_b16 v[198:199], v223 offset:4672
	s_waitcnt lgkmcnt(7)
	v_mfma_f32_32x32x16_bf16 v[48:63], v[140:143], v[112:115], 0
	v_fmamk_f32 v66, v66, 0x3e38aa3b, v163
	v_fmamk_f32 v82, v82, 0x3e38aa3b, v163
	v_exp_f32_e32 v66, v66
	v_exp_f32_e32 v82, v82
	ds_read_b128 v[140:143], v243 offset:4672
	ds_read_b64_tr_b16 v[200:201], v223 offset:9216
	ds_read_b64_tr_b16 v[202:203], v223 offset:10752
	v_mfma_f32_32x32x16_bf16 v[16:31], v[188:191], v[104:107], v[16:31]
	v_cvt_pk_bf16_f32 v96, v64, v65
	v_fmamk_f32 v67, v67, 0x3e38aa3b, v163
	v_fmamk_f32 v83, v83, 0x3e38aa3b, v163
	v_exp_f32_e32 v67, v67
	v_exp_f32_e32 v83, v83
	ds_read_b64_tr_b16 v[204:205], v223 offset:9280
	ds_read_b64_tr_b16 v[206:207], v223 offset:10816
	s_waitcnt lgkmcnt(11)
	v_mfma_f32_32x32x16_bf16 v[32:47], v[144:147], v[116:119], v[32:47]
	v_fmamk_f32 v68, v68, 0x3e38aa3b, v163
	v_fmamk_f32 v84, v84, 0x3e38aa3b, v163
	v_exp_f32_e32 v68, v68
	v_exp_f32_e32 v84, v84
	ds_read_b128 v[144:147], v243 offset:96
	v_mfma_f32_16x16x32_bf16 v[226:229], v[246:249], v[104:107], v[226:229]
	v_cvt_pk_bf16_f32 v104, v80, v81
	v_cvt_pk_bf16_f32 v97, v66, v67
	v_cvt_pk_bf16_f32 v105, v82, v83
	v_fmamk_f32 v69, v69, 0x3e38aa3b, v163
	v_fmamk_f32 v85, v85, 0x3e38aa3b, v163
	v_exp_f32_e32 v69, v69
	v_exp_f32_e32 v85, v85
	s_waitcnt lgkmcnt(11)
	v_mfma_f32_32x32x16_bf16 v[48:63], v[148:151], v[116:119], v[48:63]
	v_fmamk_f32 v70, v70, 0x3e38aa3b, v163
	v_fmamk_f32 v86, v86, 0x3e38aa3b, v163
	v_exp_f32_e32 v70, v70
	v_exp_f32_e32 v86, v86
	ds_read_b128 v[148:151], v243 offset:4704
	s_waitcnt lgkmcnt(9)
	v_mfma_f32_32x32x16_bf16 v[0:15], v[192:195], v[100:103], v[0:15]
	v_cvt_pk_bf16_f32 v98, v68, v69
	v_cvt_pk_bf16_f32 v106, v84, v85
	v_fmamk_f32 v71, v71, 0x3e38aa3b, v163
	v_fmamk_f32 v87, v87, 0x3e38aa3b, v163
	v_exp_f32_e32 v71, v71
	v_exp_f32_e32 v87, v87
	v_mfma_f32_32x32x16_bf16 v[32:47], v[136:139], v[120:123], v[32:47]
	v_fmamk_f32 v72, v72, 0x3e38aa3b, v163
	v_fmamk_f32 v88, v88, 0x3e38aa3b, v163
	v_exp_f32_e32 v72, v72
	v_exp_f32_e32 v88, v88
	s_waitcnt vmcnt(2)
	ds_write_b128 v218, v[208:211] offset:9216
	s_waitcnt vmcnt(1)
	ds_write_b128 v224, v[212:215]
	s_waitcnt lgkmcnt(9)
	v_mfma_f32_32x32x16_bf16 v[16:31], v[196:199], v[100:103], v[16:31]
	v_cvt_pk_bf16_f32 v99, v70, v71
	v_cvt_pk_bf16_f32 v107, v86, v87
	v_fmamk_f32 v73, v73, 0x3e38aa3b, v163
	v_fmamk_f32 v89, v89, 0x3e38aa3b, v163
	v_exp_f32_e32 v73, v73
	s_waitcnt lgkmcnt(8)
	v_mfma_f32_32x32x16_bf16 v[48:63], v[140:143], v[120:123], v[48:63]
	v_exp_f32_e32 v89, v89
	v_fmamk_f32 v74, v74, 0x3e38aa3b, v163
	v_fmamk_f32 v90, v90, 0x3e38aa3b, v163
	v_exp_f32_e32 v74, v74
	v_exp_f32_e32 v90, v90
	v_mfma_f32_16x16x32_bf16 v[226:229], v[246:249], v[100:103], v[226:229]
	v_cvt_pk_bf16_f32 v100, v72, v73
	v_fmamk_f32 v75, v75, 0x3e38aa3b, v163
	v_fmamk_f32 v91, v91, 0x3e38aa3b, v163
	v_exp_f32_e32 v75, v75
	v_exp_f32_e32 v91, v91
	ds_read_b64_tr_b16 v[176:177], v222 offset:0
	ds_read_b64_tr_b16 v[178:179], v222 offset:1536
	s_waitcnt lgkmcnt(5)
	v_mfma_f32_32x32x16_bf16 v[32:47], v[144:147], v[124:127], v[32:47]
	v_fmamk_f32 v76, v76, 0x3e38aa3b, v163
	v_fmamk_f32 v92, v92, 0x3e38aa3b, v163
	v_exp_f32_e32 v76, v76
	v_exp_f32_e32 v92, v92
	ds_read_b64_tr_b16 v[180:181], v222 offset:64
	ds_read_b64_tr_b16 v[182:183], v222 offset:1600
	v_mfma_f32_32x32x16_bf16 v[0:15], v[200:203], v[108:111], v[0:15]
	v_cvt_pk_bf16_f32 v101, v74, v75
	v_fmamk_f32 v77, v77, 0x3e38aa3b, v163
	v_fmamk_f32 v93, v93, 0x3e38aa3b, v163
	v_exp_f32_e32 v77, v77
	v_exp_f32_e32 v93, v93
	ds_read_b64_tr_b16 v[184:185], v222 offset:6144
	ds_read_b64_tr_b16 v[186:187], v222 offset:7680
	s_waitcnt lgkmcnt(8)
	v_mfma_f32_32x32x16_bf16 v[48:63], v[148:151], v[124:127], v[48:63]
	v_fmamk_f32 v78, v78, 0x3e38aa3b, v163
	v_fmamk_f32 v94, v94, 0x3e38aa3b, v163
	v_exp_f32_e32 v78, v78
	v_exp_f32_e32 v94, v94
	ds_read_b64_tr_b16 v[188:189], v222 offset:6208
	ds_read_b64_tr_b16 v[190:191], v222 offset:7744
	v_mfma_f32_32x32x16_bf16 v[16:31], v[204:207], v[108:111], v[16:31]
	v_cvt_pk_bf16_f32 v102, v76, v77
	v_fmamk_f32 v79, v79, 0x3e38aa3b, v163
	v_fmamk_f32 v95, v95, 0x3e38aa3b, v163
	v_exp_f32_e32 v79, v79
	v_exp_f32_e32 v95, v95
	v_mfma_f32_16x16x32_bf16 v[226:229], v[246:249], v[108:111], v[226:229]
	v_cvt_pk_bf16_f32 v108, v88, v89
	v_cvt_pk_bf16_f32 v109, v90, v91
	v_cvt_pk_bf16_f32 v110, v92, v93
	v_cvt_pk_bf16_f32 v103, v78, v79
	v_cvt_pk_bf16_f32 v111, v94, v95
	s_cmp_lg_u32 s9, 0
	s_cbranch_scc0 .Lagqa_noresc_7
	s_nop 15
	v_pk_mul_f32 v[0:1], v[0:1], v[166:167] op_sel_hi:[1,0]
	v_pk_mul_f32 v[2:3], v[2:3], v[166:167] op_sel_hi:[1,0]
	v_pk_mul_f32 v[4:5], v[4:5], v[166:167] op_sel_hi:[1,0]
	v_pk_mul_f32 v[6:7], v[6:7], v[166:167] op_sel_hi:[1,0]
	v_pk_mul_f32 v[8:9], v[8:9], v[166:167] op_sel_hi:[1,0]
	v_pk_mul_f32 v[10:11], v[10:11], v[166:167] op_sel_hi:[1,0]
	v_pk_mul_f32 v[12:13], v[12:13], v[166:167] op_sel_hi:[1,0]
	v_pk_mul_f32 v[14:15], v[14:15], v[166:167] op_sel_hi:[1,0]
	v_pk_mul_f32 v[16:17], v[16:17], v[166:167] op_sel_hi:[1,0]
	v_pk_mul_f32 v[18:19], v[18:19], v[166:167] op_sel_hi:[1,0]
	v_pk_mul_f32 v[20:21], v[20:21], v[166:167] op_sel_hi:[1,0]
	v_pk_mul_f32 v[22:23], v[22:23], v[166:167] op_sel_hi:[1,0]
	v_pk_mul_f32 v[24:25], v[24:25], v[166:167] op_sel_hi:[1,0]
	v_pk_mul_f32 v[26:27], v[26:27], v[166:167] op_sel_hi:[1,0]
	v_pk_mul_f32 v[28:29], v[28:29], v[166:167] op_sel_hi:[1,0]
	v_pk_mul_f32 v[30:31], v[30:31], v[166:167] op_sel_hi:[1,0]
	ds_bpermute_b32 v173, v231, v166
	v_mul_f32_e32 v226, v226, v166
	s_waitcnt lgkmcnt(0)
	v_mul_f32_e32 v227, v227, v173
.Lagqa_noresc_7:
	s_waitcnt lgkmcnt(8)
	s_barrier
	ds_read_b128 v[136:139], v243 offset:9216
	ds_read_b128 v[140:143], v243 offset:13824
	ds_read_b128 v[144:147], v243 offset:9248
	ds_read_b128 v[148:151], v243 offset:13856
	s_waitcnt lgkmcnt(10)
	v_mfma_f32_32x32x16_bf16 v[0:15], v[176:179], v[96:99], v[0:15]
	v_max3_f32 v168, v32, v33, v34
	v_max3_f32 v170, v48, v49, v50
	v_max3_f32 v168, v168, v35, v36
	v_max3_f32 v170, v170, v51, v52
	v_max3_f32 v168, v168, v37, v38
	v_max3_f32 v170, v170, v53, v54
	v_max3_f32 v168, v168, v39, v40
	s_mov_b32 s55, s52
	s_mov_b32 s52, s53
	s_mov_b32 s53, s54
	s_mov_b32 s54, s55
	s_mov_b32 s9, 0
	s_waitcnt lgkmcnt(8)
	v_mfma_f32_32x32x16_bf16 v[16:31], v[180:183], v[96:99], v[16:31]
	v_max3_f32 v170, v170, v55, v56
	v_max3_f32 v168, v168, v41, v42
	v_max3_f32 v170, v170, v57, v58
	v_max3_f32 v168, v168, v43, v44
	v_max3_f32 v170, v170, v59, v60
	v_max3_f32 v168, v168, v45, v46
	v_max3_f32 v170, v170, v61, v62
	v_add_u32_e32 v223, s53, v220
	v_add_u32_e32 v224, s54, v221
	v_mfma_f32_16x16x32_bf16 v[226:229], v[246:249], v[96:99], v[226:229]
	v_max_f32_e32 v168, v168, v47
	v_max_f32_e32 v170, v170, v63
	v_max_f32_e32 v168, v168, v170
	v_mov_b32_e32 v170, v168
	s_nop 1
	v_permlane32_swap_b32_e32 v168, v170
	v_max_f32_e32 v168, v168, v170
	v_mul_f32_e32 v168, 0x3e38aa3b, v168
	s_waitcnt lgkmcnt(3)
	v_mfma_f32_32x32x16_bf16 v[64:79], v[136:139], v[112:115], 0
	v_cmp_gt_f32_e32 vcc, v168, v164
	s_cbranch_vccz .Lagqa_nors_8
	v_max_f32_e32 v170, v162, v168
	v_sub_f32_e32 v166, v162, v170
	v_exp_f32_e32 v166, v166
	v_mov_b32_e32 v162, v170
	v_add_f32_e32 v164, 0x41000000, v170
	v_xor_b32_e32 v163, 0x80000000, v170
	s_mov_b32 s9, 1
.Lagqa_nors_8:
	v_fmamk_f32 v32, v32, 0x3e38aa3b, v163
	v_fmamk_f32 v48, v48, 0x3e38aa3b, v163
	v_exp_f32_e32 v32, v32
	ds_read_b128 v[136:139], v243 offset:9280
	ds_read_b64_tr_b16 v[192:193], v222 offset:3072
	ds_read_b64_tr_b16 v[194:195], v222 offset:4608
	v_mfma_f32_32x32x16_bf16 v[0:15], v[184:187], v[104:107], v[0:15]
	v_exp_f32_e32 v48, v48
	v_fmamk_f32 v33, v33, 0x3e38aa3b, v163
	v_fmamk_f32 v49, v49, 0x3e38aa3b, v163
	v_exp_f32_e32 v33, v33
	v_exp_f32_e32 v49, v49
	ds_read_b64_tr_b16 v[196:197], v222 offset:3136
	ds_read_b64_tr_b16 v[198:199], v222 offset:4672
	s_waitcnt lgkmcnt(7)
	v_mfma_f32_32x32x16_bf16 v[80:95], v[140:143], v[112:115], 0
	v_fmamk_f32 v34, v34, 0x3e38aa3b, v163
	v_fmamk_f32 v50, v50, 0x3e38aa3b, v163
	v_exp_f32_e32 v34, v34
	v_exp_f32_e32 v50, v50
	ds_read_b128 v[140:143], v243 offset:13888
	ds_read_b64_tr_b16 v[200:201], v222 offset:9216
	ds_read_b64_tr_b16 v[202:203], v222 offset:10752
	v_mfma_f32_32x32x16_bf16 v[16:31], v[188:191], v[104:107], v[16:31]
	v_cvt_pk_bf16_f32 v96, v32, v33
	v_fmamk_f32 v35, v35, 0x3e38aa3b, v163
	v_fmamk_f32 v51, v51, 0x3e38aa3b, v163
	v_exp_f32_e32 v35, v35
	v_exp_f32_e32 v51, v51
	ds_read_b64_tr_b16 v[204:205], v222 offset:9280
	ds_read_b64_tr_b16 v[206:207], v222 offset:10816
	s_waitcnt lgkmcnt(11)
	v_mfma_f32_32x32x16_bf16 v[64:79], v[144:147], v[116:119], v[64:79]
	v_fmamk_f32 v36, v36, 0x3e38aa3b, v163
	v_fmamk_f32 v52, v52, 0x3e38aa3b, v163
	v_exp_f32_e32 v36, v36
	v_exp_f32_e32 v52, v52
	ds_read_b128 v[144:147], v243 offset:9312
	v_mfma_f32_16x16x32_bf16 v[226:229], v[246:249], v[104:107], v[226:229]
	v_cvt_pk_bf16_f32 v104, v48, v49
	v_cvt_pk_bf16_f32 v97, v34, v35
	v_cvt_pk_bf16_f32 v105, v50, v51
	v_fmamk_f32 v37, v37, 0x3e38aa3b, v163
	v_fmamk_f32 v53, v53, 0x3e38aa3b, v163
	v_exp_f32_e32 v37, v37
	v_exp_f32_e32 v53, v53
	s_waitcnt lgkmcnt(11)
	v_mfma_f32_32x32x16_bf16 v[80:95], v[148:151], v[116:119], v[80:95]
	v_fmamk_f32 v38, v38, 0x3e38aa3b, v163
	v_fmamk_f32 v54, v54, 0x3e38aa3b, v163
	v_exp_f32_e32 v38, v38
	v_exp_f32_e32 v54, v54
	ds_read_b128 v[148:151], v243 offset:13920
	s_waitcnt lgkmcnt(9)
	v_mfma_f32_32x32x16_bf16 v[0:15], v[192:195], v[100:103], v[0:15]
	v_cvt_pk_bf16_f32 v98, v36, v37
	v_cvt_pk_bf16_f32 v106, v52, v53
	v_fmamk_f32 v39, v39, 0x3e38aa3b, v163
	v_fmamk_f32 v55, v55, 0x3e38aa3b, v163
	v_exp_f32_e32 v39, v39
	v_exp_f32_e32 v55, v55
	v_mfma_f32_32x32x16_bf16 v[64:79], v[136:139], v[120:123], v[64:79]
	v_fmamk_f32 v40, v40, 0x3e38aa3b, v163
	v_fmamk_f32 v56, v56, 0x3e38aa3b, v163
	v_exp_f32_e32 v40, v40
	v_exp_f32_e32 v56, v56
	s_waitcnt vmcnt(0)
	ds_write_b128 v224, v[156:159]
	s_waitcnt lgkmcnt(8)
	v_mfma_f32_32x32x16_bf16 v[16:31], v[196:199], v[100:103], v[16:31]
	v_cvt_pk_bf16_f32 v99, v38, v39
	v_cvt_pk_bf16_f32 v107, v54, v55
	v_fmamk_f32 v41, v41, 0x3e38aa3b, v163
	v_fmamk_f32 v57, v57, 0x3e38aa3b, v163
	v_exp_f32_e32 v41, v41
	s_waitcnt lgkmcnt(7)
	v_mfma_f32_32x32x16_bf16 v[80:95], v[140:143], v[120:123], v[80:95]
	v_exp_f32_e32 v57, v57
	v_fmamk_f32 v42, v42, 0x3e38aa3b, v163
	v_fmamk_f32 v58, v58, 0x3e38aa3b, v163
	v_exp_f32_e32 v42, v42
	v_exp_f32_e32 v58, v58
	v_mfma_f32_16x16x32_bf16 v[226:229], v[246:249], v[100:103], v[226:229]
	v_cvt_pk_bf16_f32 v100, v40, v41
	v_fmamk_f32 v43, v43, 0x3e38aa3b, v163
	v_fmamk_f32 v59, v59, 0x3e38aa3b, v163
	v_exp_f32_e32 v43, v43
	v_exp_f32_e32 v59, v59
	ds_read_b64_tr_b16 v[176:177], v223 offset:0
	ds_read_b64_tr_b16 v[178:179], v223 offset:1536
	s_waitcnt lgkmcnt(4)
	v_mfma_f32_32x32x16_bf16 v[64:79], v[144:147], v[124:127], v[64:79]
	v_fmamk_f32 v44, v44, 0x3e38aa3b, v163
	v_fmamk_f32 v60, v60, 0x3e38aa3b, v163
	v_exp_f32_e32 v44, v44
	v_exp_f32_e32 v60, v60
	ds_read_b64_tr_b16 v[180:181], v223 offset:64
	ds_read_b64_tr_b16 v[182:183], v223 offset:1600
	v_mfma_f32_32x32x16_bf16 v[0:15], v[200:203], v[108:111], v[0:15]
	v_cvt_pk_bf16_f32 v101, v42, v43
	v_fmamk_f32 v45, v45, 0x3e38aa3b, v163
	v_fmamk_f32 v61, v61, 0x3e38aa3b, v163
	v_exp_f32_e32 v45, v45
	v_exp_f32_e32 v61, v61
	ds_read_b64_tr_b16 v[184:185], v223 offset:6144
	ds_read_b64_tr_b16 v[186:187], v223 offset:7680
	s_waitcnt lgkmcnt(7)
	v_mfma_f32_32x32x16_bf16 v[80:95], v[148:151], v[124:127], v[80:95]
	v_fmamk_f32 v46, v46, 0x3e38aa3b, v163
	v_fmamk_f32 v62, v62, 0x3e38aa3b, v163
	v_exp_f32_e32 v46, v46
	v_exp_f32_e32 v62, v62
	ds_read_b64_tr_b16 v[188:189], v223 offset:6208
	ds_read_b64_tr_b16 v[190:191], v223 offset:7744
	v_mfma_f32_32x32x16_bf16 v[16:31], v[204:207], v[108:111], v[16:31]
	v_cvt_pk_bf16_f32 v102, v44, v45
	v_fmamk_f32 v47, v47, 0x3e38aa3b, v163
	v_fmamk_f32 v63, v63, 0x3e38aa3b, v163
	v_exp_f32_e32 v47, v47
	v_exp_f32_e32 v63, v63
	v_mfma_f32_16x16x32_bf16 v[226:229], v[246:249], v[108:111], v[226:229]
	v_cvt_pk_bf16_f32 v108, v56, v57
	v_cvt_pk_bf16_f32 v109, v58, v59
	v_cvt_pk_bf16_f32 v110, v60, v61
	v_cvt_pk_bf16_f32 v103, v46, v47
	v_cvt_pk_bf16_f32 v111, v62, v63
	s_cmp_lg_u32 s9, 0
	s_cbranch_scc0 .Lagqa_noresc_9
	s_nop 15
	v_pk_mul_f32 v[0:1], v[0:1], v[166:167] op_sel_hi:[1,0]
	v_pk_mul_f32 v[2:3], v[2:3], v[166:167] op_sel_hi:[1,0]
	v_pk_mul_f32 v[4:5], v[4:5], v[166:167] op_sel_hi:[1,0]
	v_pk_mul_f32 v[6:7], v[6:7], v[166:167] op_sel_hi:[1,0]
	v_pk_mul_f32 v[8:9], v[8:9], v[166:167] op_sel_hi:[1,0]
	v_pk_mul_f32 v[10:11], v[10:11], v[166:167] op_sel_hi:[1,0]
	v_pk_mul_f32 v[12:13], v[12:13], v[166:167] op_sel_hi:[1,0]
	v_pk_mul_f32 v[14:15], v[14:15], v[166:167] op_sel_hi:[1,0]
	v_pk_mul_f32 v[16:17], v[16:17], v[166:167] op_sel_hi:[1,0]
	v_pk_mul_f32 v[18:19], v[18:19], v[166:167] op_sel_hi:[1,0]
	v_pk_mul_f32 v[20:21], v[20:21], v[166:167] op_sel_hi:[1,0]
	v_pk_mul_f32 v[22:23], v[22:23], v[166:167] op_sel_hi:[1,0]
	v_pk_mul_f32 v[24:25], v[24:25], v[166:167] op_sel_hi:[1,0]
	v_pk_mul_f32 v[26:27], v[26:27], v[166:167] op_sel_hi:[1,0]
	v_pk_mul_f32 v[28:29], v[28:29], v[166:167] op_sel_hi:[1,0]
	v_pk_mul_f32 v[30:31], v[30:31], v[166:167] op_sel_hi:[1,0]
	ds_bpermute_b32 v173, v231, v166
	v_mul_f32_e32 v226, v226, v166
	s_waitcnt lgkmcnt(0)
	v_mul_f32_e32 v227, v227, v173

; #define AT_STEP(SC0, SC1, SN0, SN1, t, DOK, DOV) do { \
;             if (DOK) AT_GLOADK(((t) + 2) * 64); \
;             if (DOV) { AT_GLOADV(((t) + 1) * 64); AT_QK(SN0, SN1, ((t) + 1) & 1); } \
;             AT_SMPV(SC0, SC1, (t) & 1); \
;             if (DOK) AT_WRITEK((t) & 1); \
;             if (DOV) AT_WRITEV(((t) + 1) & 1); \
;             __syncthreads(); } while (0)
; template <bool MLA>
; DI void attn_phase(const int TID, const int BID, LAS unsigned char* lds, const Params& p, bool need_ctx) {
;     ...
;         AT_STEP(sb0, sb1, sa0, sa1, t + 1, false, false);
.Lagqa_nors_10:
	v_add_u32_e32 v222, s53, v220
	v_mfma_f32_16x16x32_bf16 v[226:229], v[246:249], v[96:99], v[226:229]
	v_fmamk_f32 v64, v64, 0x3e38aa3b, v163
	v_fmamk_f32 v80, v80, 0x3e38aa3b, v163
	v_exp_f32_e32 v64, v64
	v_exp_f32_e32 v80, v80
	v_fmamk_f32 v65, v65, 0x3e38aa3b, v163
	v_fmamk_f32 v81, v81, 0x3e38aa3b, v163
	v_exp_f32_e32 v65, v65
	v_exp_f32_e32 v81, v81
	s_waitcnt lgkmcnt(10)
	v_mfma_f32_32x32x16_bf16 v[0:15], v[184:187], v[104:107], v[0:15]
	v_fmamk_f32 v66, v66, 0x3e38aa3b, v163
	v_fmamk_f32 v82, v82, 0x3e38aa3b, v163
	v_exp_f32_e32 v66, v66
	v_exp_f32_e32 v82, v82
	v_cvt_pk_bf16_f32 v96, v64, v65
	v_fmamk_f32 v67, v67, 0x3e38aa3b, v163
	v_fmamk_f32 v83, v83, 0x3e38aa3b, v163
	v_exp_f32_e32 v67, v67
	s_waitcnt lgkmcnt(8)
	v_mfma_f32_32x32x16_bf16 v[16:31], v[188:191], v[104:107], v[16:31]
	v_exp_f32_e32 v83, v83
	v_fmamk_f32 v68, v68, 0x3e38aa3b, v163
	v_fmamk_f32 v84, v84, 0x3e38aa3b, v163
	v_exp_f32_e32 v68, v68
	v_exp_f32_e32 v84, v84
	v_cvt_pk_bf16_f32 v97, v66, v67
	v_fmamk_f32 v69, v69, 0x3e38aa3b, v163
	v_fmamk_f32 v85, v85, 0x3e38aa3b, v163
	v_mfma_f32_16x16x32_bf16 v[226:229], v[246:249], v[104:107], v[226:229]
	v_cvt_pk_bf16_f32 v104, v80, v81
	v_cvt_pk_bf16_f32 v105, v82, v83
	v_exp_f32_e32 v69, v69
	v_exp_f32_e32 v85, v85
	v_fmamk_f32 v70, v70, 0x3e38aa3b, v163
	v_fmamk_f32 v86, v86, 0x3e38aa3b, v163
	v_exp_f32_e32 v70, v70
	v_exp_f32_e32 v86, v86
	v_cvt_pk_bf16_f32 v98, v68, v69
	s_waitcnt lgkmcnt(6)
	v_mfma_f32_32x32x16_bf16 v[0:15], v[192:195], v[100:103], v[0:15]
	v_cvt_pk_bf16_f32 v106, v84, v85
	v_fmamk_f32 v71, v71, 0x3e38aa3b, v163
	v_fmamk_f32 v87, v87, 0x3e38aa3b, v163
	v_exp_f32_e32 v71, v71
	v_exp_f32_e32 v87, v87
	v_fmamk_f32 v72, v72, 0x3e38aa3b, v163
	v_fmamk_f32 v88, v88, 0x3e38aa3b, v163
	v_exp_f32_e32 v72, v72
	ds_read_b64_tr_b16 v[176:177], v222 offset:0
	ds_read_b64_tr_b16 v[178:179], v222 offset:1536
	s_waitcnt lgkmcnt(6)
	v_mfma_f32_32x32x16_bf16 v[16:31], v[196:199], v[100:103], v[16:31]
	v_exp_f32_e32 v88, v88
	v_cvt_pk_bf16_f32 v99, v70, v71
	v_cvt_pk_bf16_f32 v107, v86, v87
	v_fmamk_f32 v73, v73, 0x3e38aa3b, v163
	v_fmamk_f32 v89, v89, 0x3e38aa3b, v163
	v_exp_f32_e32 v73, v73
	v_exp_f32_e32 v89, v89
	v_fmamk_f32 v74, v74, 0x3e38aa3b, v163
	ds_read_b64_tr_b16 v[180:181], v222 offset:64
	ds_read_b64_tr_b16 v[182:183], v222 offset:1600
	v_mfma_f32_16x16x32_bf16 v[226:229], v[246:249], v[100:103], v[226:229]
	v_fmamk_f32 v90, v90, 0x3e38aa3b, v163
	v_exp_f32_e32 v74, v74
	v_exp_f32_e32 v90, v90
	v_cvt_pk_bf16_f32 v100, v72, v73
	v_fmamk_f32 v75, v75, 0x3e38aa3b, v163
	v_fmamk_f32 v91, v91, 0x3e38aa3b, v163
	v_exp_f32_e32 v75, v75
	v_exp_f32_e32 v91, v91
	ds_read_b64_tr_b16 v[184:185], v222 offset:6144
	ds_read_b64_tr_b16 v[186:187], v222 offset:7680
	s_waitcnt lgkmcnt(8)
	v_mfma_f32_32x32x16_bf16 v[0:15], v[200:203], v[108:111], v[0:15]
	v_fmamk_f32 v76, v76, 0x3e38aa3b, v163
	v_fmamk_f32 v92, v92, 0x3e38aa3b, v163
	v_exp_f32_e32 v76, v76
	v_exp_f32_e32 v92, v92
	v_cvt_pk_bf16_f32 v101, v74, v75
	v_fmamk_f32 v77, v77, 0x3e38aa3b, v163
	v_fmamk_f32 v93, v93, 0x3e38aa3b, v163
	v_exp_f32_e32 v77, v77
	ds_read_b64_tr_b16 v[188:189], v222 offset:6208
	ds_read_b64_tr_b16 v[190:191], v222 offset:7744
	s_waitcnt lgkmcnt(8)
	v_mfma_f32_32x32x16_bf16 v[16:31], v[204:207], v[108:111], v[16:31]
	v_exp_f32_e32 v93, v93
	v_fmamk_f32 v78, v78, 0x3e38aa3b, v163
	v_fmamk_f32 v94, v94, 0x3e38aa3b, v163
	v_exp_f32_e32 v78, v78
	v_exp_f32_e32 v94, v94
	v_cvt_pk_bf16_f32 v102, v76, v77
	v_fmamk_f32 v79, v79, 0x3e38aa3b, v163
	v_fmamk_f32 v95, v95, 0x3e38aa3b, v163
	v_mfma_f32_16x16x32_bf16 v[226:229], v[246:249], v[108:111], v[226:229]
	v_cvt_pk_bf16_f32 v108, v88, v89
	v_cvt_pk_bf16_f32 v109, v90, v91
	v_cvt_pk_bf16_f32 v110, v92, v93
	v_exp_f32_e32 v79, v79
	v_exp_f32_e32 v95, v95
	v_cvt_pk_bf16_f32 v103, v78, v79
	v_cvt_pk_bf16_f32 v111, v94, v95
	s_cmp_lg_u32 s9, 0
	s_cbranch_scc0 .Lagqa_noresc_11
	s_nop 15
	v_pk_mul_f32 v[0:1], v[0:1], v[166:167] op_sel_hi:[1,0]
	v_pk_mul_f32 v[2:3], v[2:3], v[166:167] op_sel_hi:[1,0]
	v_pk_mul_f32 v[4:5], v[4:5], v[166:167] op_sel_hi:[1,0]
	v_pk_mul_f32 v[6:7], v[6:7], v[166:167] op_sel_hi:[1,0]
	v_pk_mul_f32 v[8:9], v[8:9], v[166:167] op_sel_hi:[1,0]
	v_pk_mul_f32 v[10:11], v[10:11], v[166:167] op_sel_hi:[1,0]
	v_pk_mul_f32 v[12:13], v[12:13], v[166:167] op_sel_hi:[1,0]
	v_pk_mul_f32 v[14:15], v[14:15], v[166:167] op_sel_hi:[1,0]
	v_pk_mul_f32 v[16:17], v[16:17], v[166:167] op_sel_hi:[1,0]
	v_pk_mul_f32 v[18:19], v[18:19], v[166:167] op_sel_hi:[1,0]
	v_pk_mul_f32 v[20:21], v[20:21], v[166:167] op_sel_hi:[1,0]
	v_pk_mul_f32 v[22:23], v[22:23], v[166:167] op_sel_hi:[1,0]
	v_pk_mul_f32 v[24:25], v[24:25], v[166:167] op_sel_hi:[1,0]
	v_pk_mul_f32 v[26:27], v[26:27], v[166:167] op_sel_hi:[1,0]
	v_pk_mul_f32 v[28:29], v[28:29], v[166:167] op_sel_hi:[1,0]
	v_pk_mul_f32 v[30:31], v[30:31], v[166:167] op_sel_hi:[1,0]
	ds_bpermute_b32 v173, v231, v166
	v_mul_f32_e32 v226, v226, v166
	s_waitcnt lgkmcnt(0)
	v_mul_f32_e32 v227, v227, v173
